# K-loop: B-side LDS read address kept in one scratch VGPR, 0x4000/0x8000/0xc000 folded into ds_read offsets (3 VALU adds per iteration removed) + 3 more scalar-base loads; previous edits
# speedup vs baseline: 1.0060x; 1.0042x over previous
; #define PG8_STAGE(bufoff, gbase, voff) do { _Pragma("unroll") for (int _i = 0; _i < 2; ++_i) \
;         __builtin_amdgcn_global_load_lds((const unsigned*)((const char*)(gbase) + (voff)[_i]), (LAS unsigned*)(lds + (bufoff) + ldsw + _i * 8192), 16, 0, 0); } while (0)
; #define PG8_LDA(dst, b, h) do { _Pragma("unroll") for (int m = 0; m < 4; ++m) _Pragma("unroll") for (int k = 0; k < 2; ++k) dst[m][k] = *(const LAS f16x8*)(lds + PG8_SA(b, h) + aoff + m * 2048 + k * 1024); } while (0)
; #define PG8_LDB(dst, b, h) do { _Pragma("unroll") for (int n = 0; n < 2; ++n) _Pragma("unroll") for (int k = 0; k < 2; ++k) dst[n][k] = *(const LAS f16x8*)(lds + PG8_SB(b, h) + boff + n * 2048 + k * 1024); } while (0)
; #define PG8_MMA(ai, bj, At, Bt) do { __builtin_amdgcn_s_setprio(1); _Pragma("unroll") for (int m = 0; m < 4; ++m) _Pragma("unroll") for (int n = 0; n < 2; ++n) _Pragma("unroll") for (int k = 0; k < 2; ++k) \
;         acc[ai][bj][m][n] = __builtin_amdgcn_mfma_f32_16x16x32_f16(Bt[n][k], At[m][k], acc[ai][bj][m][n], 0, 0, 0); __builtin_amdgcn_s_setprio(0); } while (0)
; #define PG8_WAIT_V(n) asm volatile("s_waitcnt vmcnt(" #n ")" ::: "memory")
; #define PG8_WAIT_L(n) asm volatile("s_waitcnt lgkmcnt(" #n ")" ::: "memory")
; #define PG8_BAR __builtin_amdgcn_s_barrier()
; #define PG8_SCHED __builtin_amdgcn_sched_barrier(0)
; template <class Epi>
; __device__ __forceinline__ void gemm_phase(LAS unsigned char* lds, const Gemm g0, const StaticOrder& S, const Epi& E) {
;     ...
;             const char* a1 = cA + (size_t)(t + 1) * kstep;
;             const char* a2 = last ? nA : cA + (size_t)(t + 2) * kstep; const char* b2 = last ? nB : cB + (size_t)(t + 2) * kstep;
;             const char* a3 = a2 + kstep; const char* b3 = b2 + kstep;
;             PG8_LDB(B0, 0, 0); PG8_SCHED; PG8_LDA(At, 0, 0); PG8_STAGE(PG8_SA(1, 1), a1 + hstep, voffA);
;             PG8_WAIT_L(8); PG8_BAR; PG8_WAIT_L(0); PG8_MMA(0, 0, At, B0); PG8_BAR; PG8_SCHED;
;             PG8_LDB(B1, 0, 1); PG8_STAGE(PG8_SB(0, 0), b2, voffB);
;             PG8_BAR; PG8_WAIT_L(0); PG8_MMA(0, 1, At, B1); PG8_BAR;
;             PG8_LDA(At, 0, 1); PG8_STAGE(PG8_SA(0, 0), a2, voffA);
;             PG8_BAR; PG8_WAIT_L(0); PG8_MMA(1, 0, At, B0); PG8_BAR; PG8_SCHED;
;             PG8_STAGE(PG8_SB(0, 1), b2 + hstep, voffB);
;             PG8_WAIT_V(6); PG8_BAR; PG8_MMA(1, 1, At, B1); PG8_BAR;
.LBB0_198:
	s_add_u32 s52, s0, 0xfff80080
	s_addc_u32 s53, s1, -1
	s_and_b64 s[22:23], s[50:51], exec
	s_cselect_b32 s53, s75, s53
	s_cselect_b32 s52, s80, s52
	s_add_i32 s84, 0, 0x10000
	v_add_u32_e32 v161, s84, v214
	ds_read_b128 v[136:139], v161
	ds_read_b128 v[140:143], v161 offset:1024
	ds_read_b128 v[144:147], v161 offset:2048
	ds_read_b128 v[148:151], v161 offset:3072
	s_and_b64 s[22:23], s[50:51], exec
	s_cselect_b32 s51, s81, s25
	s_cselect_b32 s50, s82, s24
	s_add_i32 m0, s28, 0xc000
	ds_read_b128 v[152:155], v222
	ds_read_b128 v[156:159], v222 offset:1024
	ds_read_b128 v[186:189], v222 offset:2048
	ds_read_b128 v[190:193], v222 offset:3072
	ds_read_b128 v[194:197], v222 offset:4096
	ds_read_b128 v[198:201], v222 offset:5120
	ds_read_b128 v[202:205], v222 offset:6144
	ds_read_b128 v[206:209], v222 offset:7168
	global_load_lds_dwordx4 v184, s[0:1]
	s_add_i32 m0, s28, 0xe000
	s_nop 0
	global_load_lds_dwordx4 v182, s[0:1]
	s_waitcnt lgkmcnt(8)
	s_barrier
	s_waitcnt lgkmcnt(0)
	s_waitcnt lgkmcnt(0)
	v_mfma_f32_16x16x32_f16 v[126:129], v[136:139], v[152:155], v[126:129]
	v_mfma_f32_16x16x32_f16 v[122:125], v[144:147], v[152:155], v[122:125]
	v_mfma_f32_16x16x32_f16 v[118:121], v[136:139], v[186:189], v[118:121]
	v_mfma_f32_16x16x32_f16 v[110:113], v[144:147], v[186:189], v[110:113]
	v_mfma_f32_16x16x32_f16 v[102:105], v[136:139], v[194:197], v[102:105]
	v_mfma_f32_16x16x32_f16 v[98:101], v[144:147], v[194:197], v[98:101]
	v_mfma_f32_16x16x32_f16 v[86:89], v[136:139], v[202:205], v[86:89]
	v_mfma_f32_16x16x32_f16 v[82:85], v[144:147], v[202:205], v[82:85]
	v_mfma_f32_16x16x32_f16 v[126:129], v[140:143], v[156:159], v[126:129]
	v_mfma_f32_16x16x32_f16 v[122:125], v[148:151], v[156:159], v[122:125]
	v_mfma_f32_16x16x32_f16 v[118:121], v[140:143], v[190:193], v[118:121]
	v_mfma_f32_16x16x32_f16 v[110:113], v[148:151], v[190:193], v[110:113]
	v_mfma_f32_16x16x32_f16 v[102:105], v[140:143], v[198:201], v[102:105]
	v_mfma_f32_16x16x32_f16 v[98:101], v[148:151], v[198:201], v[98:101]
	v_mfma_f32_16x16x32_f16 v[86:89], v[140:143], v[206:209], v[86:89]
	v_mfma_f32_16x16x32_f16 v[82:85], v[148:151], v[206:209], v[82:85]
	s_barrier
	s_add_i32 s85, 0, 0x14000
	s_add_i32 s22, s84, s19
	ds_read_b128 v[210:213], v161 offset:16384
	ds_read_b128 v[234:237], v161 offset:17408
	ds_read_b128 v[238:241], v161 offset:18432
	ds_read_b128 v[242:245], v161 offset:19456
	v_add_u32_e32 v160, 0x80, v178
	s_mov_b32 m0, s22
	v_add_u32_e32 v162, 0x80, v174
	global_load_lds_dwordx4 v178, s[50:51]
	s_add_i32 m0, s22, 0x2000
	s_nop 0
	global_load_lds_dwordx4 v174, s[50:51]
	s_barrier
	s_waitcnt lgkmcnt(0)
	s_waitcnt lgkmcnt(0)
	v_mfma_f32_16x16x32_f16 v[114:117], v[210:213], v[152:155], v[114:117]
	v_mfma_f32_16x16x32_f16 v[106:109], v[238:241], v[152:155], v[106:109]
	v_mfma_f32_16x16x32_f16 v[94:97], v[210:213], v[186:189], v[94:97]
	v_mfma_f32_16x16x32_f16 v[90:93], v[238:241], v[186:189], v[90:93]
	v_mfma_f32_16x16x32_f16 v[78:81], v[210:213], v[194:197], v[78:81]
	v_mfma_f32_16x16x32_f16 v[74:77], v[238:241], v[194:197], v[74:77]
	v_mfma_f32_16x16x32_f16 v[70:73], v[210:213], v[202:205], v[70:73]
	v_mfma_f32_16x16x32_f16 v[66:69], v[238:241], v[202:205], v[66:69]
	v_mfma_f32_16x16x32_f16 v[114:117], v[234:237], v[156:159], v[114:117]
	v_mfma_f32_16x16x32_f16 v[106:109], v[242:245], v[156:159], v[106:109]
	v_mfma_f32_16x16x32_f16 v[94:97], v[234:237], v[190:193], v[94:97]
	v_mfma_f32_16x16x32_f16 v[90:93], v[242:245], v[190:193], v[90:93]
	v_mfma_f32_16x16x32_f16 v[78:81], v[234:237], v[198:201], v[78:81]
	v_mfma_f32_16x16x32_f16 v[74:77], v[242:245], v[198:201], v[74:77]
	v_mfma_f32_16x16x32_f16 v[70:73], v[234:237], v[206:209], v[70:73]
	v_mfma_f32_16x16x32_f16 v[66:69], v[242:245], v[206:209], v[66:69]
	s_mov_b32 m0, s28
	v_add_u32_e32 v164, 0x80, v180
	s_barrier
	ds_read_b128 v[152:155], v222 offset:16384
	ds_read_b128 v[156:159], v222 offset:17408
	ds_read_b128 v[186:189], v222 offset:18432
	ds_read_b128 v[190:193], v222 offset:19456
	ds_read_b128 v[194:197], v222 offset:20480
	ds_read_b128 v[198:201], v222 offset:21504
	ds_read_b128 v[202:205], v222 offset:22528
	ds_read_b128 v[206:209], v222 offset:23552
	global_load_lds_dwordx4 v180, s[52:53]
	v_add_u32_e32 v170, 0x80, v176
	s_mov_b32 m0, s29
	s_nop 0
	global_load_lds_dwordx4 v176, s[52:53]
	s_barrier
	s_waitcnt lgkmcnt(0)
	s_waitcnt lgkmcnt(0)
	v_mfma_f32_16x16x32_f16 v[62:65], v[136:139], v[152:155], v[62:65]
	v_mfma_f32_16x16x32_f16 v[58:61], v[144:147], v[152:155], v[58:61]
	v_mfma_f32_16x16x32_f16 v[54:57], v[136:139], v[186:189], v[54:57]
	v_mfma_f32_16x16x32_f16 v[50:53], v[144:147], v[186:189], v[50:53]
	v_mfma_f32_16x16x32_f16 v[38:41], v[136:139], v[194:197], v[38:41]
	v_mfma_f32_16x16x32_f16 v[30:33], v[144:147], v[194:197], v[30:33]
	v_mfma_f32_16x16x32_f16 v[22:25], v[136:139], v[202:205], v[22:25]
	v_mfma_f32_16x16x32_f16 v[18:21], v[144:147], v[202:205], v[18:21]
	v_mfma_f32_16x16x32_f16 v[62:65], v[140:143], v[156:159], v[62:65]
	v_mfma_f32_16x16x32_f16 v[58:61], v[148:151], v[156:159], v[58:61]
	v_mfma_f32_16x16x32_f16 v[54:57], v[140:143], v[190:193], v[54:57]
	v_mfma_f32_16x16x32_f16 v[50:53], v[148:151], v[190:193], v[50:53]
	v_mfma_f32_16x16x32_f16 v[38:41], v[140:143], v[198:201], v[38:41]
	v_mfma_f32_16x16x32_f16 v[30:33], v[148:151], v[198:201], v[30:33]
	v_mfma_f32_16x16x32_f16 v[22:25], v[140:143], v[206:209], v[22:25]
	v_mfma_f32_16x16x32_f16 v[18:21], v[148:151], v[206:209], v[18:21]
	s_barrier
	s_add_u32 s22, s50, 0x80000
	s_addc_u32 s23, s51, 0
	s_add_i32 s84, s85, s19
	s_mov_b32 m0, s84
	s_nop 0
	global_load_lds_dwordx4 v178, s[22:23]
	s_add_i32 m0, s84, 0x2000
	s_nop 0
	global_load_lds_dwordx4 v174, s[22:23]
	s_waitcnt vmcnt(6)
	s_barrier
; #define PG8_STAGE(bufoff, gbase, voff) do { _Pragma("unroll") for (int _i = 0; _i < 2; ++_i) \
;         __builtin_amdgcn_global_load_lds((const unsigned*)((const char*)(gbase) + (voff)[_i]), (LAS unsigned*)(lds + (bufoff) + ldsw + _i * 8192), 16, 0, 0); } while (0)
; #define PG8_LDA(dst, b, h) do { _Pragma("unroll") for (int m = 0; m < 4; ++m) _Pragma("unroll") for (int k = 0; k < 2; ++k) dst[m][k] = *(const LAS f16x8*)(lds + PG8_SA(b, h) + aoff + m * 2048 + k * 1024); } while (0)
; #define PG8_LDB(dst, b, h) do { _Pragma("unroll") for (int n = 0; n < 2; ++n) _Pragma("unroll") for (int k = 0; k < 2; ++k) dst[n][k] = *(const LAS f16x8*)(lds + PG8_SB(b, h) + boff + n * 2048 + k * 1024); } while (0)
; #define PG8_MMA(ai, bj, At, Bt) do { __builtin_amdgcn_s_setprio(1); _Pragma("unroll") for (int m = 0; m < 4; ++m) _Pragma("unroll") for (int n = 0; n < 2; ++n) _Pragma("unroll") for (int k = 0; k < 2; ++k) \
;         acc[ai][bj][m][n] = __builtin_amdgcn_mfma_f32_16x16x32_f16(Bt[n][k], At[m][k], acc[ai][bj][m][n], 0, 0, 0); __builtin_amdgcn_s_setprio(0); } while (0)
; #define PG8_WAIT_V(n) asm volatile("s_waitcnt vmcnt(" #n ")" ::: "memory")
; #define PG8_WAIT_L(n) asm volatile("s_waitcnt lgkmcnt(" #n ")" ::: "memory")
; #define PG8_BAR __builtin_amdgcn_s_barrier()
; #define PG8_SCHED __builtin_amdgcn_sched_barrier(0)
; template <class Epi>
; __device__ __forceinline__ void gemm_phase(LAS unsigned char* lds, const Gemm g0, const StaticOrder& S, const Epi& E) {
;     ...
;             PG8_WAIT_V(6); PG8_BAR; PG8_MMA(1, 1, At, B1); PG8_BAR;
;             PG8_LDB(B0, 1, 0); PG8_SCHED; PG8_LDA(At, 1, 0); PG8_STAGE(PG8_SA(0, 1), a2 + hstep, voffA);
;             PG8_WAIT_L(8); PG8_BAR; PG8_WAIT_L(0); PG8_MMA(0, 0, At, B0); PG8_BAR; PG8_SCHED;
;             PG8_LDB(B1, 1, 1); PG8_STAGE(PG8_SB(1, 0), b3, voffB);
;             PG8_BAR; PG8_WAIT_L(0); PG8_MMA(0, 1, At, B1); PG8_BAR;
	v_mfma_f32_16x16x32_f16 v[46:49], v[210:213], v[152:155], v[46:49]
	v_mfma_f32_16x16x32_f16 v[42:45], v[238:241], v[152:155], v[42:45]
	v_mfma_f32_16x16x32_f16 v[34:37], v[210:213], v[186:189], v[34:37]
	v_mfma_f32_16x16x32_f16 v[26:29], v[238:241], v[186:189], v[26:29]
	v_mfma_f32_16x16x32_f16 v[14:17], v[210:213], v[194:197], v[14:17]
	v_mfma_f32_16x16x32_f16 v[10:13], v[238:241], v[194:197], v[10:13]
	v_mfma_f32_16x16x32_f16 v[6:9], v[210:213], v[202:205], v[6:9]
	v_mfma_f32_16x16x32_f16 v[2:5], v[238:241], v[202:205], v[2:5]
	v_mfma_f32_16x16x32_f16 v[46:49], v[234:237], v[156:159], v[46:49]
	v_mfma_f32_16x16x32_f16 v[42:45], v[242:245], v[156:159], v[42:45]
	v_mfma_f32_16x16x32_f16 v[34:37], v[234:237], v[190:193], v[34:37]
	v_mfma_f32_16x16x32_f16 v[26:29], v[242:245], v[190:193], v[26:29]
	v_mfma_f32_16x16x32_f16 v[14:17], v[234:237], v[198:201], v[14:17]
	v_mfma_f32_16x16x32_f16 v[10:13], v[242:245], v[198:201], v[10:13]
	v_mfma_f32_16x16x32_f16 v[6:9], v[234:237], v[206:209], v[6:9]
	v_mfma_f32_16x16x32_f16 v[2:5], v[242:245], v[206:209], v[2:5]
	s_add_i32 s84, 0, 0x18000
	s_barrier
	ds_read_b128 v[136:139], v161 offset:32768
	ds_read_b128 v[140:143], v161 offset:33792
	ds_read_b128 v[144:147], v161 offset:34816
	ds_read_b128 v[148:151], v161 offset:35840
	s_add_u32 s22, s52, 0x80000
	s_addc_u32 s23, s53, 0
	s_mov_b32 m0, s31
	ds_read_b128 v[152:155], v222 offset:32768
	ds_read_b128 v[156:159], v222 offset:33792
	ds_read_b128 v[186:189], v222 offset:34816
	ds_read_b128 v[190:193], v222 offset:35840
	ds_read_b128 v[194:197], v222 offset:36864
	ds_read_b128 v[198:201], v222 offset:37888
	ds_read_b128 v[202:205], v222 offset:38912
	ds_read_b128 v[206:209], v222 offset:39936
	global_load_lds_dwordx4 v180, s[22:23]
	s_mov_b32 m0, s58
	s_nop 0
	global_load_lds_dwordx4 v176, s[22:23]
	s_waitcnt lgkmcnt(8)
	s_barrier
	s_waitcnt lgkmcnt(0)
	s_waitcnt lgkmcnt(0)
	v_mfma_f32_16x16x32_f16 v[126:129], v[136:139], v[152:155], v[126:129]
	v_mfma_f32_16x16x32_f16 v[122:125], v[144:147], v[152:155], v[122:125]
	v_mfma_f32_16x16x32_f16 v[118:121], v[136:139], v[186:189], v[118:121]
	v_mfma_f32_16x16x32_f16 v[110:113], v[144:147], v[186:189], v[110:113]
	v_mfma_f32_16x16x32_f16 v[102:105], v[136:139], v[194:197], v[102:105]
	v_mfma_f32_16x16x32_f16 v[98:101], v[144:147], v[194:197], v[98:101]
	v_mfma_f32_16x16x32_f16 v[86:89], v[136:139], v[202:205], v[86:89]
	v_mfma_f32_16x16x32_f16 v[82:85], v[144:147], v[202:205], v[82:85]
	v_mfma_f32_16x16x32_f16 v[126:129], v[140:143], v[156:159], v[126:129]
	v_mfma_f32_16x16x32_f16 v[122:125], v[148:151], v[156:159], v[122:125]
	v_mfma_f32_16x16x32_f16 v[118:121], v[140:143], v[190:193], v[118:121]
	v_mfma_f32_16x16x32_f16 v[110:113], v[148:151], v[190:193], v[110:113]
	v_mfma_f32_16x16x32_f16 v[102:105], v[140:143], v[198:201], v[102:105]
	v_mfma_f32_16x16x32_f16 v[98:101], v[148:151], v[198:201], v[98:101]
	v_mfma_f32_16x16x32_f16 v[86:89], v[140:143], v[206:209], v[86:89]
	v_mfma_f32_16x16x32_f16 v[82:85], v[148:151], v[206:209], v[82:85]
	s_barrier
	s_add_i32 s85, 0, 0x1c000
	s_add_i32 s22, s84, s19
	s_mov_b32 m0, s22
	ds_read_b128 v[210:213], v161 offset:49152
	ds_read_b128 v[234:237], v161 offset:50176
	ds_read_b128 v[238:241], v161 offset:51200
	ds_read_b128 v[242:245], v161 offset:52224
	global_load_lds_dwordx4 v160, s[50:51]
	s_add_i32 m0, s22, 0x2000
	s_nop 0
	global_load_lds_dwordx4 v162, s[50:51]
	s_barrier
; #define PG8_STAGE(bufoff, gbase, voff) do { _Pragma("unroll") for (int _i = 0; _i < 2; ++_i) \
;         __builtin_amdgcn_global_load_lds((const unsigned*)((const char*)(gbase) + (voff)[_i]), (LAS unsigned*)(lds + (bufoff) + ldsw + _i * 8192), 16, 0, 0); } while (0)
; #define PG8_LDA(dst, b, h) do { _Pragma("unroll") for (int m = 0; m < 4; ++m) _Pragma("unroll") for (int k = 0; k < 2; ++k) dst[m][k] = *(const LAS f16x8*)(lds + PG8_SA(b, h) + aoff + m * 2048 + k * 1024); } while (0)
; #define PG8_MMA(ai, bj, At, Bt) do { __builtin_amdgcn_s_setprio(1); _Pragma("unroll") for (int m = 0; m < 4; ++m) _Pragma("unroll") for (int n = 0; n < 2; ++n) _Pragma("unroll") for (int k = 0; k < 2; ++k) \
;         acc[ai][bj][m][n] = __builtin_amdgcn_mfma_f32_16x16x32_f16(Bt[n][k], At[m][k], acc[ai][bj][m][n], 0, 0, 0); __builtin_amdgcn_s_setprio(0); } while (0)
; #define PG8_WAIT_V(n) asm volatile("s_waitcnt vmcnt(" #n ")" ::: "memory")
; #define PG8_WAIT_L(n) asm volatile("s_waitcnt lgkmcnt(" #n ")" ::: "memory")
; #define PG8_BAR __builtin_amdgcn_s_barrier()
; #define PG8_SCHED __builtin_amdgcn_sched_barrier(0)
; template <class Epi>
; __device__ __forceinline__ void gemm_phase(LAS unsigned char* lds, const Gemm g0, const StaticOrder& S, const Epi& E) {
;     ...
;             PG8_BAR; PG8_WAIT_L(0); PG8_MMA(0, 1, At, B1); PG8_BAR;
;             PG8_LDA(At, 1, 1); PG8_STAGE(PG8_SA(1, 0), a3, voffA);
;             PG8_BAR; PG8_WAIT_L(0); PG8_MMA(1, 0, At, B0); PG8_BAR; PG8_SCHED;
;             PG8_STAGE(PG8_SB(1, 1), b3 + hstep, voffB);
;             PG8_WAIT_V(6); PG8_BAR; PG8_MMA(1, 1, At, B1); PG8_BAR;
;         }
	s_waitcnt lgkmcnt(0)
	s_waitcnt lgkmcnt(0)
	v_mfma_f32_16x16x32_f16 v[114:117], v[210:213], v[152:155], v[114:117]
	v_mfma_f32_16x16x32_f16 v[106:109], v[238:241], v[152:155], v[106:109]
	v_mfma_f32_16x16x32_f16 v[94:97], v[210:213], v[186:189], v[94:97]
	v_mfma_f32_16x16x32_f16 v[90:93], v[238:241], v[186:189], v[90:93]
	v_mfma_f32_16x16x32_f16 v[78:81], v[210:213], v[194:197], v[78:81]
	v_mfma_f32_16x16x32_f16 v[74:77], v[238:241], v[194:197], v[74:77]
	v_mfma_f32_16x16x32_f16 v[70:73], v[210:213], v[202:205], v[70:73]
	v_mfma_f32_16x16x32_f16 v[66:69], v[238:241], v[202:205], v[66:69]
	v_mfma_f32_16x16x32_f16 v[114:117], v[234:237], v[156:159], v[114:117]
	v_mfma_f32_16x16x32_f16 v[106:109], v[242:245], v[156:159], v[106:109]
	v_mfma_f32_16x16x32_f16 v[94:97], v[234:237], v[190:193], v[94:97]
	v_mfma_f32_16x16x32_f16 v[90:93], v[242:245], v[190:193], v[90:93]
	v_mfma_f32_16x16x32_f16 v[78:81], v[234:237], v[198:201], v[78:81]
	v_mfma_f32_16x16x32_f16 v[74:77], v[242:245], v[198:201], v[74:77]
	v_mfma_f32_16x16x32_f16 v[70:73], v[234:237], v[206:209], v[70:73]
	v_mfma_f32_16x16x32_f16 v[66:69], v[242:245], v[206:209], v[66:69]
	s_mov_b32 m0, s59
	s_barrier
	ds_read_b128 v[152:155], v222 offset:49152
	ds_read_b128 v[156:159], v222 offset:50176
	ds_read_b128 v[186:189], v222 offset:51200
	ds_read_b128 v[190:193], v222 offset:52224
	ds_read_b128 v[194:197], v222 offset:53248
	ds_read_b128 v[198:201], v222 offset:54272
	ds_read_b128 v[202:205], v222 offset:55296
	ds_read_b128 v[206:209], v222 offset:56320
	global_load_lds_dwordx4 v164, s[52:53]
	s_mov_b32 m0, s61
	s_nop 0
	global_load_lds_dwordx4 v170, s[52:53]
	s_barrier
	s_waitcnt lgkmcnt(0)
	s_waitcnt lgkmcnt(0)
	v_mfma_f32_16x16x32_f16 v[62:65], v[136:139], v[152:155], v[62:65]
	v_mfma_f32_16x16x32_f16 v[58:61], v[144:147], v[152:155], v[58:61]
	v_mfma_f32_16x16x32_f16 v[54:57], v[136:139], v[186:189], v[54:57]
	v_mfma_f32_16x16x32_f16 v[50:53], v[144:147], v[186:189], v[50:53]
	v_mfma_f32_16x16x32_f16 v[38:41], v[136:139], v[194:197], v[38:41]
	v_mfma_f32_16x16x32_f16 v[30:33], v[144:147], v[194:197], v[30:33]
	v_mfma_f32_16x16x32_f16 v[22:25], v[136:139], v[202:205], v[22:25]
	v_mfma_f32_16x16x32_f16 v[18:21], v[144:147], v[202:205], v[18:21]
	v_mfma_f32_16x16x32_f16 v[62:65], v[140:143], v[156:159], v[62:65]
	v_mfma_f32_16x16x32_f16 v[58:61], v[148:151], v[156:159], v[58:61]
	v_mfma_f32_16x16x32_f16 v[54:57], v[140:143], v[190:193], v[54:57]
	v_mfma_f32_16x16x32_f16 v[50:53], v[148:151], v[190:193], v[50:53]
	v_mfma_f32_16x16x32_f16 v[38:41], v[140:143], v[198:201], v[38:41]
	v_mfma_f32_16x16x32_f16 v[30:33], v[148:151], v[198:201], v[30:33]
	v_mfma_f32_16x16x32_f16 v[22:25], v[140:143], v[206:209], v[22:25]
	v_mfma_f32_16x16x32_f16 v[18:21], v[148:151], v[206:209], v[18:21]
	s_barrier
	s_add_u32 s22, s50, 0x80080
	s_addc_u32 s23, s51, 0
	s_add_i32 s50, s85, s19
	s_mov_b32 m0, s50
	s_nop 0
	global_load_lds_dwordx4 v178, s[22:23]
	s_add_i32 m0, s50, 0x2000
	s_nop 0
	global_load_lds_dwordx4 v174, s[22:23]
	s_waitcnt vmcnt(6)
	s_barrier
	v_mfma_f32_16x16x32_f16 v[46:49], v[210:213], v[152:155], v[46:49]
	v_mfma_f32_16x16x32_f16 v[42:45], v[238:241], v[152:155], v[42:45]
	v_mfma_f32_16x16x32_f16 v[34:37], v[210:213], v[186:189], v[34:37]
	v_mfma_f32_16x16x32_f16 v[26:29], v[238:241], v[186:189], v[26:29]
	v_mfma_f32_16x16x32_f16 v[14:17], v[210:213], v[194:197], v[14:17]
	v_mfma_f32_16x16x32_f16 v[10:13], v[238:241], v[194:197], v[10:13]
	v_mfma_f32_16x16x32_f16 v[6:9], v[210:213], v[202:205], v[6:9]
	v_mfma_f32_16x16x32_f16 v[2:5], v[238:241], v[202:205], v[2:5]
	v_mfma_f32_16x16x32_f16 v[46:49], v[234:237], v[156:159], v[46:49]
	v_mfma_f32_16x16x32_f16 v[42:45], v[242:245], v[156:159], v[42:45]
	v_mfma_f32_16x16x32_f16 v[34:37], v[234:237], v[190:193], v[34:37]
	v_mfma_f32_16x16x32_f16 v[26:29], v[242:245], v[190:193], v[26:29]
	v_mfma_f32_16x16x32_f16 v[14:17], v[234:237], v[198:201], v[14:17]
	v_mfma_f32_16x16x32_f16 v[10:13], v[242:245], v[198:201], v[10:13]
	v_mfma_f32_16x16x32_f16 v[6:9], v[234:237], v[206:209], v[6:9]
	v_mfma_f32_16x16x32_f16 v[2:5], v[242:245], v[206:209], v[2:5]
	s_add_i32 s83, s83, 2
	s_add_u32 s24, s24, 0x100
	s_addc_u32 s25, s25, 0
	s_add_u32 s0, s0, 0x100
	s_addc_u32 s1, s1, 0
	s_cmp_gt_u32 s83, 29
	s_barrier
	s_cbranch_scc1 .LBB0_201

;     __device__ __forceinline__ void prefetch(const Unit& u, int wr, int wc, int lane) const { lnfold_prefetch(vl, stats, gW, bW, u, wr, wc, lane); }
;     __device__ __forceinline__ void prefetch(const Unit& u, int wr, int wc, int lane) const { lnfold_prefetch(vl, stats, gW, bW, u, wr, wc, lane); }
; #define PG8_STAGE(bufoff, gbase, voff) do { _Pragma("unroll") for (int _i = 0; _i < 2; ++_i) \
;         __builtin_amdgcn_global_load_lds((const unsigned*)((const char*)(gbase) + (voff)[_i]), (LAS unsigned*)(lds + (bufoff) + ldsw + _i * 8192), 16, 0, 0); } while (0)
; #define PG8_LDA(dst, b, h) do { _Pragma("unroll") for (int m = 0; m < 4; ++m) _Pragma("unroll") for (int k = 0; k < 2; ++k) dst[m][k] = *(const LAS f16x8*)(lds + PG8_SA(b, h) + aoff + m * 2048 + k * 1024); } while (0)
; #define PG8_LDB(dst, b, h) do { _Pragma("unroll") for (int n = 0; n < 2; ++n) _Pragma("unroll") for (int k = 0; k < 2; ++k) dst[n][k] = *(const LAS f16x8*)(lds + PG8_SB(b, h) + boff + n * 2048 + k * 1024); } while (0)
; #define PG8_WAIT_V(n) asm volatile("s_waitcnt vmcnt(" #n ")" ::: "memory")
; #define PG8_WAIT_L(n) asm volatile("s_waitcnt lgkmcnt(" #n ")" ::: "memory")
; #define PG8_BAR __builtin_amdgcn_s_barrier()
; template <class Epi>
; __device__ __forceinline__ void gemm_phase(LAS unsigned char* lds, const Gemm g0, const StaticOrder& S, const Epi& E) {
;     ...
;             const bool last = (t == nt - 2);
;             if (Epi::PREF && last) E.prefetch(cur, wr, wc, lane);
;             const char* a1 = cA + (size_t)(t + 1) * kstep;
;             const char* a2 = last ? nA : cA + (size_t)(t + 2) * kstep; const char* b2 = last ? nB : cB + (size_t)(t + 2) * kstep;
;             const char* a3 = a2 + kstep; const char* b3 = b2 + kstep;
;             PG8_LDB(B0, 0, 0); PG8_SCHED; PG8_LDA(At, 0, 0); PG8_STAGE(PG8_SA(1, 1), a1 + hstep, voffA);
;             PG8_WAIT_L(8); PG8_BAR; PG8_WAIT_L(0); PG8_MMA(0, 0, At, B0); PG8_BAR; PG8_SCHED;
;             PG8_LDB(B1, 0, 1); PG8_STAGE(PG8_SB(0, 0), b2, voffB);
;             PG8_BAR; PG8_WAIT_L(0); PG8_MMA(0, 1, At, B1); PG8_BAR;
;             PG8_LDA(At, 0, 1); PG8_STAGE(PG8_SA(0, 0), a2, voffA);
;             PG8_BAR; PG8_WAIT_L(0); PG8_MMA(1, 0, At, B0); PG8_BAR; PG8_SCHED;
;             PG8_STAGE(PG8_SB(0, 1), b2 + hstep, voffB);
;             PG8_WAIT_V(6); PG8_BAR; PG8_MMA(1, 1, At, B1); PG8_BAR;
.LBB0_302:
	s_add_u32 s22, s6, 0xfff80080
	s_addc_u32 s23, s7, -1
	s_add_i32 s59, 0, 0x10000
	v_add_u32_e32 v161, s59, v148
	ds_read_b128 v[142:145], v161
	ds_read_b128 v[152:155], v161 offset:1024
	ds_read_b128 v[156:159], v161 offset:2048
	ds_read_b128 v[174:177], v161 offset:3072
	s_cmp_eq_u32 s58, 28
	s_cselect_b32 s37, s15, s23
	s_cselect_b32 s36, s52, s22
	s_cselect_b32 s35, s13, s53
	s_cselect_b32 s34, s24, s25
	s_add_i32 m0, s28, 0xc000
	ds_read_b128 v[178:181], v150
	ds_read_b128 v[182:185], v150 offset:1024
	ds_read_b128 v[186:189], v150 offset:2048
	ds_read_b128 v[190:193], v150 offset:3072
	ds_read_b128 v[194:197], v150 offset:4096
	ds_read_b128 v[198:201], v150 offset:5120
	ds_read_b128 v[202:205], v150 offset:6144
	ds_read_b128 v[206:209], v150 offset:7168
	global_load_lds_dwordx4 v140, s[6:7]
	s_add_i32 m0, s28, 0xe000
	s_nop 0
	global_load_lds_dwordx4 v138, s[6:7]
	s_waitcnt lgkmcnt(8)
	s_barrier
	s_waitcnt lgkmcnt(0)
	s_waitcnt lgkmcnt(0)
	v_mfma_f32_16x16x32_f16 v[126:129], v[142:145], v[178:181], v[126:129]
	v_mfma_f32_16x16x32_f16 v[122:125], v[156:159], v[178:181], v[122:125]
	v_mfma_f32_16x16x32_f16 v[110:113], v[142:145], v[186:189], v[110:113]
	v_mfma_f32_16x16x32_f16 v[106:109], v[156:159], v[186:189], v[106:109]
	v_mfma_f32_16x16x32_f16 v[94:97], v[142:145], v[194:197], v[94:97]
	v_mfma_f32_16x16x32_f16 v[90:93], v[156:159], v[194:197], v[90:93]
	v_mfma_f32_16x16x32_f16 v[78:81], v[142:145], v[202:205], v[78:81]
	v_mfma_f32_16x16x32_f16 v[74:77], v[156:159], v[202:205], v[74:77]
	v_mfma_f32_16x16x32_f16 v[126:129], v[152:155], v[182:185], v[126:129]
	v_mfma_f32_16x16x32_f16 v[122:125], v[174:177], v[182:185], v[122:125]
	v_mfma_f32_16x16x32_f16 v[110:113], v[152:155], v[190:193], v[110:113]
	v_mfma_f32_16x16x32_f16 v[106:109], v[174:177], v[190:193], v[106:109]
	v_mfma_f32_16x16x32_f16 v[94:97], v[152:155], v[198:201], v[94:97]
	v_mfma_f32_16x16x32_f16 v[90:93], v[174:177], v[198:201], v[90:93]
	v_mfma_f32_16x16x32_f16 v[78:81], v[152:155], v[206:209], v[78:81]
	v_mfma_f32_16x16x32_f16 v[74:77], v[174:177], v[206:209], v[74:77]
	s_barrier
	s_add_i32 s61, 0, 0x14000
	s_add_i32 s22, s59, s19
	ds_read_b128 v[210:213], v161 offset:16384
	ds_read_b128 v[234:237], v161 offset:17408
	ds_read_b128 v[238:241], v161 offset:18432
	ds_read_b128 v[242:245], v161 offset:19456
	v_add_u32_e32 v146, 0x80, v134
	s_mov_b32 m0, s22
	v_add_u32_e32 v160, 0x80, v130
	global_load_lds_dwordx4 v134, s[34:35]
	s_add_i32 m0, s22, 0x2000
	s_nop 0
	global_load_lds_dwordx4 v130, s[34:35]
	s_barrier
	s_waitcnt lgkmcnt(0)
	s_waitcnt lgkmcnt(0)
	v_mfma_f32_16x16x32_f16 v[118:121], v[210:213], v[178:181], v[118:121]
	v_mfma_f32_16x16x32_f16 v[114:117], v[238:241], v[178:181], v[114:117]
	v_mfma_f32_16x16x32_f16 v[102:105], v[210:213], v[186:189], v[102:105]
	v_mfma_f32_16x16x32_f16 v[98:101], v[238:241], v[186:189], v[98:101]
	v_mfma_f32_16x16x32_f16 v[86:89], v[210:213], v[194:197], v[86:89]
	v_mfma_f32_16x16x32_f16 v[82:85], v[238:241], v[194:197], v[82:85]
	v_mfma_f32_16x16x32_f16 v[70:73], v[210:213], v[202:205], v[70:73]
	v_mfma_f32_16x16x32_f16 v[66:69], v[238:241], v[202:205], v[66:69]
	v_mfma_f32_16x16x32_f16 v[118:121], v[234:237], v[182:185], v[118:121]
	v_mfma_f32_16x16x32_f16 v[114:117], v[242:245], v[182:185], v[114:117]
	v_mfma_f32_16x16x32_f16 v[102:105], v[234:237], v[190:193], v[102:105]
	v_mfma_f32_16x16x32_f16 v[98:101], v[242:245], v[190:193], v[98:101]
	v_mfma_f32_16x16x32_f16 v[86:89], v[234:237], v[198:201], v[86:89]
	v_mfma_f32_16x16x32_f16 v[82:85], v[242:245], v[198:201], v[82:85]
	v_mfma_f32_16x16x32_f16 v[70:73], v[234:237], v[206:209], v[70:73]
	v_mfma_f32_16x16x32_f16 v[66:69], v[242:245], v[206:209], v[66:69]
	s_mov_b32 m0, s28
	v_add_u32_e32 v162, 0x80, v136
	s_barrier
	ds_read_b128 v[178:181], v150 offset:16384
	ds_read_b128 v[182:185], v150 offset:17408
	ds_read_b128 v[186:189], v150 offset:18432
	ds_read_b128 v[190:193], v150 offset:19456
	ds_read_b128 v[194:197], v150 offset:20480
	ds_read_b128 v[198:201], v150 offset:21504
	ds_read_b128 v[202:205], v150 offset:22528
	ds_read_b128 v[206:209], v150 offset:23552
	global_load_lds_dwordx4 v136, s[36:37]
	v_add_u32_e32 v164, 0x80, v132
	s_mov_b32 m0, s29
	s_nop 0
	global_load_lds_dwordx4 v132, s[36:37]
	s_barrier
	s_waitcnt lgkmcnt(0)
	s_waitcnt lgkmcnt(0)
	v_mfma_f32_16x16x32_f16 v[62:65], v[142:145], v[178:181], v[62:65]
	v_mfma_f32_16x16x32_f16 v[58:61], v[156:159], v[178:181], v[58:61]
	v_mfma_f32_16x16x32_f16 v[46:49], v[142:145], v[186:189], v[46:49]
	v_mfma_f32_16x16x32_f16 v[42:45], v[156:159], v[186:189], v[42:45]
	v_mfma_f32_16x16x32_f16 v[30:33], v[142:145], v[194:197], v[30:33]
	v_mfma_f32_16x16x32_f16 v[26:29], v[156:159], v[194:197], v[26:29]
	v_mfma_f32_16x16x32_f16 v[14:17], v[142:145], v[202:205], v[14:17]
	v_mfma_f32_16x16x32_f16 v[10:13], v[156:159], v[202:205], v[10:13]
	v_mfma_f32_16x16x32_f16 v[62:65], v[152:155], v[182:185], v[62:65]
	v_mfma_f32_16x16x32_f16 v[58:61], v[174:177], v[182:185], v[58:61]
	v_mfma_f32_16x16x32_f16 v[46:49], v[152:155], v[190:193], v[46:49]
	v_mfma_f32_16x16x32_f16 v[42:45], v[174:177], v[190:193], v[42:45]
	v_mfma_f32_16x16x32_f16 v[30:33], v[152:155], v[198:201], v[30:33]
	v_mfma_f32_16x16x32_f16 v[26:29], v[174:177], v[198:201], v[26:29]
	v_mfma_f32_16x16x32_f16 v[14:17], v[152:155], v[206:209], v[14:17]
	v_mfma_f32_16x16x32_f16 v[10:13], v[174:177], v[206:209], v[10:13]
	s_barrier
	s_add_u32 s22, s34, 0x80000
	s_addc_u32 s23, s35, 0
	s_add_i32 s59, s61, s19
	s_mov_b32 m0, s59
	s_nop 0
	global_load_lds_dwordx4 v134, s[22:23]
	s_add_i32 m0, s59, 0x2000
	s_nop 0
	global_load_lds_dwordx4 v130, s[22:23]
	s_waitcnt vmcnt(6)
	s_barrier
; #define PG8_STAGE(bufoff, gbase, voff) do { _Pragma("unroll") for (int _i = 0; _i < 2; ++_i) \
;         __builtin_amdgcn_global_load_lds((const unsigned*)((const char*)(gbase) + (voff)[_i]), (LAS unsigned*)(lds + (bufoff) + ldsw + _i * 8192), 16, 0, 0); } while (0)
; #define PG8_LDA(dst, b, h) do { _Pragma("unroll") for (int m = 0; m < 4; ++m) _Pragma("unroll") for (int k = 0; k < 2; ++k) dst[m][k] = *(const LAS f16x8*)(lds + PG8_SA(b, h) + aoff + m * 2048 + k * 1024); } while (0)
; #define PG8_LDB(dst, b, h) do { _Pragma("unroll") for (int n = 0; n < 2; ++n) _Pragma("unroll") for (int k = 0; k < 2; ++k) dst[n][k] = *(const LAS f16x8*)(lds + PG8_SB(b, h) + boff + n * 2048 + k * 1024); } while (0)
; #define PG8_MMA(ai, bj, At, Bt) do { __builtin_amdgcn_s_setprio(1); _Pragma("unroll") for (int m = 0; m < 4; ++m) _Pragma("unroll") for (int n = 0; n < 2; ++n) _Pragma("unroll") for (int k = 0; k < 2; ++k) \
;         acc[ai][bj][m][n] = __builtin_amdgcn_mfma_f32_16x16x32_f16(Bt[n][k], At[m][k], acc[ai][bj][m][n], 0, 0, 0); __builtin_amdgcn_s_setprio(0); } while (0)
; #define PG8_WAIT_V(n) asm volatile("s_waitcnt vmcnt(" #n ")" ::: "memory")
; #define PG8_WAIT_L(n) asm volatile("s_waitcnt lgkmcnt(" #n ")" ::: "memory")
; #define PG8_BAR __builtin_amdgcn_s_barrier()
; #define PG8_SCHED __builtin_amdgcn_sched_barrier(0)
; template <class Epi>
; __device__ __forceinline__ void gemm_phase(LAS unsigned char* lds, const Gemm g0, const StaticOrder& S, const Epi& E) {
;     ...
;             PG8_WAIT_V(6); PG8_BAR; PG8_MMA(1, 1, At, B1); PG8_BAR;
;             PG8_LDB(B0, 1, 0); PG8_SCHED; PG8_LDA(At, 1, 0); PG8_STAGE(PG8_SA(0, 1), a2 + hstep, voffA);
;             PG8_WAIT_L(8); PG8_BAR; PG8_WAIT_L(0); PG8_MMA(0, 0, At, B0); PG8_BAR; PG8_SCHED;
;             PG8_LDB(B1, 1, 1); PG8_STAGE(PG8_SB(1, 0), b3, voffB);
;             PG8_BAR; PG8_WAIT_L(0); PG8_MMA(0, 1, At, B1); PG8_BAR;
;             PG8_LDA(At, 1, 1); PG8_STAGE(PG8_SA(1, 0), a3, voffA);
;             PG8_BAR; PG8_WAIT_L(0); PG8_MMA(1, 0, At, B0); PG8_BAR; PG8_SCHED;
	v_mfma_f32_16x16x32_f16 v[54:57], v[210:213], v[178:181], v[54:57]
	v_mfma_f32_16x16x32_f16 v[50:53], v[238:241], v[178:181], v[50:53]
	v_mfma_f32_16x16x32_f16 v[38:41], v[210:213], v[186:189], v[38:41]
	v_mfma_f32_16x16x32_f16 v[34:37], v[238:241], v[186:189], v[34:37]
	v_mfma_f32_16x16x32_f16 v[22:25], v[210:213], v[194:197], v[22:25]
	v_mfma_f32_16x16x32_f16 v[18:21], v[238:241], v[194:197], v[18:21]
	v_mfma_f32_16x16x32_f16 v[6:9], v[210:213], v[202:205], v[6:9]
	v_mfma_f32_16x16x32_f16 v[2:5], v[238:241], v[202:205], v[2:5]
	v_mfma_f32_16x16x32_f16 v[54:57], v[234:237], v[182:185], v[54:57]
	v_mfma_f32_16x16x32_f16 v[50:53], v[242:245], v[182:185], v[50:53]
	v_mfma_f32_16x16x32_f16 v[38:41], v[234:237], v[190:193], v[38:41]
	v_mfma_f32_16x16x32_f16 v[34:37], v[242:245], v[190:193], v[34:37]
	v_mfma_f32_16x16x32_f16 v[22:25], v[234:237], v[198:201], v[22:25]
	v_mfma_f32_16x16x32_f16 v[18:21], v[242:245], v[198:201], v[18:21]
	v_mfma_f32_16x16x32_f16 v[6:9], v[234:237], v[206:209], v[6:9]
	v_mfma_f32_16x16x32_f16 v[2:5], v[242:245], v[206:209], v[2:5]
	s_add_i32 s59, 0, 0x18000
	s_barrier
	ds_read_b128 v[142:145], v161 offset:32768
	ds_read_b128 v[152:155], v161 offset:33792
	ds_read_b128 v[156:159], v161 offset:34816
	ds_read_b128 v[174:177], v161 offset:35840
	s_add_u32 s22, s36, 0x80000
	s_addc_u32 s23, s37, 0
	s_mov_b32 m0, s31
	ds_read_b128 v[178:181], v150 offset:32768
	ds_read_b128 v[182:185], v150 offset:33792
	ds_read_b128 v[186:189], v150 offset:34816
	ds_read_b128 v[190:193], v150 offset:35840
	ds_read_b128 v[194:197], v150 offset:36864
	ds_read_b128 v[198:201], v150 offset:37888
	ds_read_b128 v[202:205], v150 offset:38912
	ds_read_b128 v[206:209], v150 offset:39936
	global_load_lds_dwordx4 v136, s[22:23]
	s_mov_b32 m0, s38
	s_nop 0
	global_load_lds_dwordx4 v132, s[22:23]
	s_waitcnt lgkmcnt(8)
	s_barrier
	s_waitcnt lgkmcnt(0)
	s_waitcnt lgkmcnt(0)
	v_mfma_f32_16x16x32_f16 v[126:129], v[142:145], v[178:181], v[126:129]
	v_mfma_f32_16x16x32_f16 v[122:125], v[156:159], v[178:181], v[122:125]
	v_mfma_f32_16x16x32_f16 v[110:113], v[142:145], v[186:189], v[110:113]
	v_mfma_f32_16x16x32_f16 v[106:109], v[156:159], v[186:189], v[106:109]
	v_mfma_f32_16x16x32_f16 v[94:97], v[142:145], v[194:197], v[94:97]
	v_mfma_f32_16x16x32_f16 v[90:93], v[156:159], v[194:197], v[90:93]
	v_mfma_f32_16x16x32_f16 v[78:81], v[142:145], v[202:205], v[78:81]
	v_mfma_f32_16x16x32_f16 v[74:77], v[156:159], v[202:205], v[74:77]
	v_mfma_f32_16x16x32_f16 v[126:129], v[152:155], v[182:185], v[126:129]
	v_mfma_f32_16x16x32_f16 v[122:125], v[174:177], v[182:185], v[122:125]
	v_mfma_f32_16x16x32_f16 v[110:113], v[152:155], v[190:193], v[110:113]
	v_mfma_f32_16x16x32_f16 v[106:109], v[174:177], v[190:193], v[106:109]
	v_mfma_f32_16x16x32_f16 v[94:97], v[152:155], v[198:201], v[94:97]
	v_mfma_f32_16x16x32_f16 v[90:93], v[174:177], v[198:201], v[90:93]
	v_mfma_f32_16x16x32_f16 v[78:81], v[152:155], v[206:209], v[78:81]
	v_mfma_f32_16x16x32_f16 v[74:77], v[174:177], v[206:209], v[74:77]
	s_barrier
	s_add_i32 s61, 0, 0x1c000
	s_add_i32 s22, s59, s19
	s_mov_b32 m0, s22
	ds_read_b128 v[210:213], v161 offset:49152
	ds_read_b128 v[234:237], v161 offset:50176
	ds_read_b128 v[238:241], v161 offset:51200
	ds_read_b128 v[242:245], v161 offset:52224
	global_load_lds_dwordx4 v146, s[34:35]
	s_add_i32 m0, s22, 0x2000
	s_nop 0
	global_load_lds_dwordx4 v160, s[34:35]
	s_barrier
	s_waitcnt lgkmcnt(0)
	s_waitcnt lgkmcnt(0)
	v_mfma_f32_16x16x32_f16 v[118:121], v[210:213], v[178:181], v[118:121]
	v_mfma_f32_16x16x32_f16 v[114:117], v[238:241], v[178:181], v[114:117]
	v_mfma_f32_16x16x32_f16 v[102:105], v[210:213], v[186:189], v[102:105]
	v_mfma_f32_16x16x32_f16 v[98:101], v[238:241], v[186:189], v[98:101]
	v_mfma_f32_16x16x32_f16 v[86:89], v[210:213], v[194:197], v[86:89]
	v_mfma_f32_16x16x32_f16 v[82:85], v[238:241], v[194:197], v[82:85]
	v_mfma_f32_16x16x32_f16 v[70:73], v[210:213], v[202:205], v[70:73]
	v_mfma_f32_16x16x32_f16 v[66:69], v[238:241], v[202:205], v[66:69]
	v_mfma_f32_16x16x32_f16 v[118:121], v[234:237], v[182:185], v[118:121]
	v_mfma_f32_16x16x32_f16 v[114:117], v[242:245], v[182:185], v[114:117]
	v_mfma_f32_16x16x32_f16 v[102:105], v[234:237], v[190:193], v[102:105]
	v_mfma_f32_16x16x32_f16 v[98:101], v[242:245], v[190:193], v[98:101]
	v_mfma_f32_16x16x32_f16 v[86:89], v[234:237], v[198:201], v[86:89]
	v_mfma_f32_16x16x32_f16 v[82:85], v[242:245], v[198:201], v[82:85]
	v_mfma_f32_16x16x32_f16 v[70:73], v[234:237], v[206:209], v[70:73]
	v_mfma_f32_16x16x32_f16 v[66:69], v[242:245], v[206:209], v[66:69]
	s_mov_b32 m0, s39
	s_barrier
	ds_read_b128 v[178:181], v150 offset:49152
	ds_read_b128 v[182:185], v150 offset:50176
	ds_read_b128 v[186:189], v150 offset:51200
	ds_read_b128 v[190:193], v150 offset:52224
	ds_read_b128 v[194:197], v150 offset:53248
	ds_read_b128 v[198:201], v150 offset:54272
	ds_read_b128 v[202:205], v150 offset:55296
	ds_read_b128 v[206:209], v150 offset:56320
	global_load_lds_dwordx4 v162, s[36:37]
	s_mov_b32 m0, s48
	s_nop 0
	global_load_lds_dwordx4 v164, s[36:37]
	s_barrier
; __device__ __forceinline__ float gelu_tanh(float x) { const float y = 1.5957691216057308f * (x + 0.044715f * x * x * x); return x * fast_rcp(1.0f + __expf(-y)); }
; #define PG8_STAGE(bufoff, gbase, voff) do { _Pragma("unroll") for (int _i = 0; _i < 2; ++_i) \
;         __builtin_amdgcn_global_load_lds((const unsigned*)((const char*)(gbase) + (voff)[_i]), (LAS unsigned*)(lds + (bufoff) + ldsw + _i * 8192), 16, 0, 0); } while (0)
; #define PG8_MMA(ai, bj, At, Bt) do { __builtin_amdgcn_s_setprio(1); _Pragma("unroll") for (int m = 0; m < 4; ++m) _Pragma("unroll") for (int n = 0; n < 2; ++n) _Pragma("unroll") for (int k = 0; k < 2; ++k) \
;         acc[ai][bj][m][n] = __builtin_amdgcn_mfma_f32_16x16x32_f16(Bt[n][k], At[m][k], acc[ai][bj][m][n], 0, 0, 0); __builtin_amdgcn_s_setprio(0); } while (0)
; #define PG8_WAIT_V(n) asm volatile("s_waitcnt vmcnt(" #n ")" ::: "memory")
; #define PG8_WAIT_L(n) asm volatile("s_waitcnt lgkmcnt(" #n ")" ::: "memory")
; #define PG8_BAR __builtin_amdgcn_s_barrier()
; #define PG8_SCHED __builtin_amdgcn_sched_barrier(0)
;     __device__ __forceinline__ void operator()(f32x4 (&acc)[2][2][4][2], const Unit& u, int wr, int wc, int fr, int fq) const {
;     ...
;             for (int m = 0; m < 4; ++m) { h16* rowp = dst + (size_t)(row0 + ai * HALF + m * 16) * DM + colb;
; #pragma unroll
;                 for (int bj = 0; bj < 2; ++bj) { f32x4 v0 = acc[ai][bj][m][0], v1 = acc[ai][bj][m][1];
;                     if (isy) {
; #pragma unroll
;                         for (int j = 0; j < 4; ++j) { v0[j] = gelu_tanh(v0[j]); v1[j] = gelu_tanh(v1[j]); } }
;                     u32x4 w; w.x = pk2(v0[0], v0[1]); w.y = pk2(v0[2], v0[3]); w.z = pk2(v1[0], v1[1]); w.w = pk2(v1[2], v1[3]);
; template <class Epi>
; __device__ __forceinline__ void gemm_phase(LAS unsigned char* lds, const Gemm g0, const StaticOrder& S, const Epi& E) {
;     ...
;             PG8_BAR; PG8_WAIT_L(0); PG8_MMA(1, 0, At, B0); PG8_BAR; PG8_SCHED;
;             PG8_STAGE(PG8_SB(1, 1), b3 + hstep, voffB);
;             PG8_WAIT_V(6); PG8_BAR; PG8_MMA(1, 1, At, B1); PG8_BAR;
	s_waitcnt lgkmcnt(0)
	s_waitcnt lgkmcnt(0)
	v_mfma_f32_16x16x32_f16 v[62:65], v[142:145], v[178:181], v[62:65]
	v_mfma_f32_16x16x32_f16 v[58:61], v[156:159], v[178:181], v[58:61]
	v_mfma_f32_16x16x32_f16 v[46:49], v[142:145], v[186:189], v[46:49]
	v_mfma_f32_16x16x32_f16 v[42:45], v[156:159], v[186:189], v[42:45]
	v_mfma_f32_16x16x32_f16 v[30:33], v[142:145], v[194:197], v[30:33]
	v_mfma_f32_16x16x32_f16 v[26:29], v[156:159], v[194:197], v[26:29]
	v_mfma_f32_16x16x32_f16 v[14:17], v[142:145], v[202:205], v[14:17]
	v_mfma_f32_16x16x32_f16 v[10:13], v[156:159], v[202:205], v[10:13]
	v_mfma_f32_16x16x32_f16 v[62:65], v[152:155], v[182:185], v[62:65]
	v_mfma_f32_16x16x32_f16 v[58:61], v[174:177], v[182:185], v[58:61]
	v_mfma_f32_16x16x32_f16 v[46:49], v[152:155], v[190:193], v[46:49]
	v_mfma_f32_16x16x32_f16 v[42:45], v[174:177], v[190:193], v[42:45]
	v_mfma_f32_16x16x32_f16 v[30:33], v[152:155], v[198:201], v[30:33]
	v_mfma_f32_16x16x32_f16 v[26:29], v[174:177], v[198:201], v[26:29]
	v_mfma_f32_16x16x32_f16 v[14:17], v[152:155], v[206:209], v[14:17]
	v_mfma_f32_16x16x32_f16 v[10:13], v[174:177], v[206:209], v[10:13]
	s_barrier
	s_add_u32 s22, s34, 0x80080
	s_addc_u32 s23, s35, 0
	s_add_i32 s34, s61, s19
	s_mov_b32 m0, s34
	s_nop 0
	global_load_lds_dwordx4 v134, s[22:23]
	s_add_i32 m0, s34, 0x2000
	s_nop 0
	global_load_lds_dwordx4 v130, s[22:23]
	s_waitcnt vmcnt(6)
	s_barrier
	v_mfma_f32_16x16x32_f16 v[54:57], v[210:213], v[178:181], v[54:57]
	v_mfma_f32_16x16x32_f16 v[50:53], v[238:241], v[178:181], v[50:53]
	v_mfma_f32_16x16x32_f16 v[38:41], v[210:213], v[186:189], v[38:41]
	v_mfma_f32_16x16x32_f16 v[34:37], v[238:241], v[186:189], v[34:37]
	v_mfma_f32_16x16x32_f16 v[22:25], v[210:213], v[194:197], v[22:25]
	v_mfma_f32_16x16x32_f16 v[18:21], v[238:241], v[194:197], v[18:21]
	v_mfma_f32_16x16x32_f16 v[6:9], v[210:213], v[202:205], v[6:9]
	v_mfma_f32_16x16x32_f16 v[2:5], v[238:241], v[202:205], v[2:5]
	v_mfma_f32_16x16x32_f16 v[54:57], v[234:237], v[182:185], v[54:57]
	v_mfma_f32_16x16x32_f16 v[50:53], v[242:245], v[182:185], v[50:53]
	v_mfma_f32_16x16x32_f16 v[38:41], v[234:237], v[190:193], v[38:41]
	v_mfma_f32_16x16x32_f16 v[34:37], v[242:245], v[190:193], v[34:37]
	v_mfma_f32_16x16x32_f16 v[22:25], v[234:237], v[198:201], v[22:25]
	v_mfma_f32_16x16x32_f16 v[18:21], v[242:245], v[198:201], v[18:21]
	v_mfma_f32_16x16x32_f16 v[6:9], v[234:237], v[206:209], v[6:9]
	v_mfma_f32_16x16x32_f16 v[2:5], v[242:245], v[206:209], v[2:5]
	s_add_i32 s58, s58, 2
	s_add_u32 s25, s25, 0x100
	s_addc_u32 s53, s53, 0
	s_add_u32 s6, s6, 0x100
	s_addc_u32 s7, s7, 0
	s_cmp_gt_u32 s58, 29
	s_barrier
	s_cbranch_scc0 .LBB0_302
	s_cmp_lt_i32 s51, 8
	s_cselect_b64 s[34:35], -1, 0
	s_cmp_gt_i32 s51, 7
	s_cbranch_scc1 .LBB0_305
	v_mul_f32_e32 v143, 0x3d372713, v122
	v_mul_f32_e32 v143, v122, v143
	v_fma_f32 v143, v122, v143, v122
	v_mul_f32_e32 v143, 0xbfcc422a, v143
	v_mul_f32_e32 v143, 0x3fb8aa3b, v143
	v_exp_f32_e32 v143, v143
	v_mul_f32_e32 v142, 0x3d372713, v126
	v_mul_f32_e32 v142, v126, v142
	v_fma_f32 v142, v126, v142, v126
	v_add_f32_e32 v143, 1.0, v143
	v_rcp_f32_e32 v144, v143
	v_mul_f32_e32 v143, 0x3d372713, v127
	v_mul_f32_e32 v143, v127, v143
	v_fma_f32 v143, v127, v143, v127
	v_mul_f32_e32 v142, 0xbfcc422a, v142
	v_mul_f32_e32 v143, 0xbfcc422a, v143
	v_mul_f32_e32 v142, 0x3fb8aa3b, v142
	v_mul_f32_e32 v143, 0x3fb8aa3b, v143
	v_mul_f32_e32 v147, 0x3d372713, v124
	v_exp_f32_e32 v142, v142
	v_exp_f32_e32 v143, v143
	v_mul_f32_e32 v147, v124, v147
	v_fma_f32 v147, v124, v147, v124
	v_mul_f32_e32 v147, 0xbfcc422a, v147
	v_mul_f32_e32 v147, 0x3fb8aa3b, v147
	v_add_f32_e32 v142, 1.0, v142
	v_add_f32_e32 v143, 1.0, v143
	v_exp_f32_e32 v147, v147
	v_rcp_f32_e32 v142, v142
	v_rcp_f32_e32 v143, v143
	v_mul_f32_e32 v145, 0x3d372713, v123
	v_add_f32_e32 v147, 1.0, v147
	v_mul_f32_e32 v146, 0x3d372713, v128
	v_rcp_f32_e32 v152, v147
	v_mul_f32_e32 v147, 0x3d372713, v129
	v_pk_mul_f32 v[126:127], v[126:127], v[142:143]
	v_mul_f32_e32 v142, 0x3d372713, v125
	v_mul_f32_e32 v145, v123, v145
	v_mul_f32_e32 v146, v128, v146
	v_mul_f32_e32 v147, v129, v147
	v_mul_f32_e32 v142, v125, v142
	v_fma_f32 v145, v123, v145, v123
	v_fma_f32 v146, v128, v146, v128
	v_fma_f32 v147, v129, v147, v129
	v_fma_f32 v142, v125, v142, v125
	v_mul_f32_e32 v145, 0xbfcc422a, v145
	v_mul_f32_e32 v146, 0xbfcc422a, v146
	v_mul_f32_e32 v147, 0xbfcc422a, v147
	v_mul_f32_e32 v142, 0xbfcc422a, v142
	v_mul_f32_e32 v145, 0x3fb8aa3b, v145
	v_mul_f32_e32 v146, 0x3fb8aa3b, v146
	v_mul_f32_e32 v147, 0x3fb8aa3b, v147
	v_mul_f32_e32 v142, 0x3fb8aa3b, v142
	v_exp_f32_e32 v145, v145
	v_exp_f32_e32 v146, v146
	v_exp_f32_e32 v147, v147
	v_exp_f32_e32 v142, v142
	v_add_f32_e32 v145, 1.0, v145
	v_add_f32_e32 v146, 1.0, v146
	v_add_f32_e32 v147, 1.0, v147
	v_add_f32_e32 v142, 1.0, v142
	v_rcp_f32_e32 v145, v145
	v_rcp_f32_e32 v146, v146
	v_rcp_f32_e32 v147, v147
	v_rcp_f32_e32 v153, v142
	v_pk_mul_f32 v[122:123], v[122:123], v[144:145]
	v_pk_mul_f32 v[128:129], v[128:129], v[146:147]
	v_pk_mul_f32 v[124:125], v[124:125], v[152:153]

;     __device__ __forceinline__ void prefetch(const Unit& u, int wr, int wc, int lane) const { lnfold_prefetch(vl, stats, gW, bW, u, wr, wc, lane); }
;     __device__ __forceinline__ void prefetch(const Unit& u, int wr, int wc, int lane) const { lnfold_prefetch(vl, stats, gW, bW, u, wr, wc, lane); }
; #define PG8_STAGE(bufoff, gbase, voff) do { _Pragma("unroll") for (int _i = 0; _i < 2; ++_i) \
;         __builtin_amdgcn_global_load_lds((const unsigned*)((const char*)(gbase) + (voff)[_i]), (LAS unsigned*)(lds + (bufoff) + ldsw + _i * 8192), 16, 0, 0); } while (0)
; #define PG8_LDA(dst, b, h) do { _Pragma("unroll") for (int m = 0; m < 4; ++m) _Pragma("unroll") for (int k = 0; k < 2; ++k) dst[m][k] = *(const LAS f16x8*)(lds + PG8_SA(b, h) + aoff + m * 2048 + k * 1024); } while (0)
; #define PG8_LDB(dst, b, h) do { _Pragma("unroll") for (int n = 0; n < 2; ++n) _Pragma("unroll") for (int k = 0; k < 2; ++k) dst[n][k] = *(const LAS f16x8*)(lds + PG8_SB(b, h) + boff + n * 2048 + k * 1024); } while (0)
; #define PG8_WAIT_V(n) asm volatile("s_waitcnt vmcnt(" #n ")" ::: "memory")
; #define PG8_WAIT_L(n) asm volatile("s_waitcnt lgkmcnt(" #n ")" ::: "memory")
; #define PG8_BAR __builtin_amdgcn_s_barrier()
; template <class Epi>
; __device__ __forceinline__ void gemm_phase(LAS unsigned char* lds, const Gemm g0, const StaticOrder& S, const Epi& E) {
;     ...
;             const bool last = (t == nt - 2);
;             if (Epi::PREF && last) E.prefetch(cur, wr, wc, lane);
;             const char* a1 = cA + (size_t)(t + 1) * kstep;
;             const char* a2 = last ? nA : cA + (size_t)(t + 2) * kstep; const char* b2 = last ? nB : cB + (size_t)(t + 2) * kstep;
;             const char* a3 = a2 + kstep; const char* b3 = b2 + kstep;
;             PG8_LDB(B0, 0, 0); PG8_SCHED; PG8_LDA(At, 0, 0); PG8_STAGE(PG8_SA(1, 1), a1 + hstep, voffA);
;             PG8_WAIT_L(8); PG8_BAR; PG8_WAIT_L(0); PG8_MMA(0, 0, At, B0); PG8_BAR; PG8_SCHED;
;             PG8_LDB(B1, 0, 1); PG8_STAGE(PG8_SB(0, 0), b2, voffB);
;             PG8_BAR; PG8_WAIT_L(0); PG8_MMA(0, 1, At, B1); PG8_BAR;
;             PG8_LDA(At, 0, 1); PG8_STAGE(PG8_SA(0, 0), a2, voffA);
;             PG8_BAR; PG8_WAIT_L(0); PG8_MMA(1, 0, At, B0); PG8_BAR; PG8_SCHED;
;             PG8_STAGE(PG8_SB(0, 1), b2 + hstep, voffB);
;             PG8_WAIT_V(6); PG8_BAR; PG8_MMA(1, 1, At, B1); PG8_BAR;
.LBB0_512:
	s_add_u32 s23, s12, 0xfff80080
	s_addc_u32 s48, s13, -1
	s_add_i32 s90, 0, 0x10000
	v_add_u32_e32 v165, s90, v205
	ds_read_b128 v[122:125], v165
	ds_read_b128 v[126:129], v165 offset:1024
	ds_read_b128 v[138:141], v165 offset:2048
	ds_read_b128 v[142:145], v165 offset:3072
	s_cmp_eq_u32 s22, 28
	s_cselect_b32 s51, s15, s48
	s_cselect_b32 s50, s24, s23
	s_cselect_b32 s49, s25, vcc_hi
	s_cselect_b32 s48, s53, vcc_lo
	s_add_i32 m0, s71, 0xc000
	ds_read_b128 v[146:149], v210
	ds_read_b128 v[150:153], v210 offset:1024
	ds_read_b128 v[154:157], v210 offset:2048
	ds_read_b128 v[158:161], v210 offset:3072
	ds_read_b128 v[188:191], v210 offset:4096
	ds_read_b128 v[192:195], v210 offset:5120
	ds_read_b128 v[196:199], v210 offset:6144
	ds_read_b128 v[200:203], v210 offset:7168
	global_load_lds_dwordx4 v186, s[12:13]
	s_add_i32 m0, s71, 0xe000
	s_nop 0
	global_load_lds_dwordx4 v184, s[12:13]
	s_waitcnt lgkmcnt(8)
	s_barrier
	s_waitcnt lgkmcnt(0)
	s_waitcnt lgkmcnt(0)
	v_mfma_f32_16x16x32_f16 v[134:137], v[122:125], v[146:149], v[134:137]
	v_mfma_f32_16x16x32_f16 v[130:133], v[138:141], v[146:149], v[130:133]
	v_mfma_f32_16x16x32_f16 v[110:113], v[122:125], v[154:157], v[110:113]
	v_mfma_f32_16x16x32_f16 v[106:109], v[138:141], v[154:157], v[106:109]
	v_mfma_f32_16x16x32_f16 v[94:97], v[122:125], v[188:191], v[94:97]
	v_mfma_f32_16x16x32_f16 v[90:93], v[138:141], v[188:191], v[90:93]
	v_mfma_f32_16x16x32_f16 v[78:81], v[122:125], v[196:199], v[78:81]
	v_mfma_f32_16x16x32_f16 v[74:77], v[138:141], v[196:199], v[74:77]
	v_mfma_f32_16x16x32_f16 v[134:137], v[126:129], v[150:153], v[134:137]
	v_mfma_f32_16x16x32_f16 v[130:133], v[142:145], v[150:153], v[130:133]
	v_mfma_f32_16x16x32_f16 v[110:113], v[126:129], v[158:161], v[110:113]
	v_mfma_f32_16x16x32_f16 v[106:109], v[142:145], v[158:161], v[106:109]
	v_mfma_f32_16x16x32_f16 v[94:97], v[126:129], v[192:195], v[94:97]
	v_mfma_f32_16x16x32_f16 v[90:93], v[142:145], v[192:195], v[90:93]
	v_mfma_f32_16x16x32_f16 v[78:81], v[126:129], v[200:203], v[78:81]
	v_mfma_f32_16x16x32_f16 v[74:77], v[142:145], v[200:203], v[74:77]
	s_barrier
	s_add_i32 s23, 0, 0x14000
	s_add_i32 s90, s90, s75
	ds_read_b128 v[212:215], v165 offset:16384
	ds_read_b128 v[234:237], v165 offset:17408
	ds_read_b128 v[238:241], v165 offset:18432
	ds_read_b128 v[242:245], v165 offset:19456
	v_add_u32_e32 v162, 0x80, v178
	s_mov_b32 m0, s90
	v_add_u32_e32 v164, 0x80, v174
	global_load_lds_dwordx4 v178, s[48:49]
	s_add_i32 m0, s90, 0x2000
	s_nop 0
	global_load_lds_dwordx4 v174, s[48:49]
	s_barrier
	s_waitcnt lgkmcnt(0)
	s_waitcnt lgkmcnt(0)
	v_mfma_f32_16x16x32_f16 v[118:121], v[212:215], v[146:149], v[118:121]
	v_mfma_f32_16x16x32_f16 v[114:117], v[238:241], v[146:149], v[114:117]
	v_mfma_f32_16x16x32_f16 v[102:105], v[212:215], v[154:157], v[102:105]
	v_mfma_f32_16x16x32_f16 v[98:101], v[238:241], v[154:157], v[98:101]
	v_mfma_f32_16x16x32_f16 v[86:89], v[212:215], v[188:191], v[86:89]
	v_mfma_f32_16x16x32_f16 v[82:85], v[238:241], v[188:191], v[82:85]
	v_mfma_f32_16x16x32_f16 v[70:73], v[212:215], v[196:199], v[70:73]
	v_mfma_f32_16x16x32_f16 v[66:69], v[238:241], v[196:199], v[66:69]
	v_mfma_f32_16x16x32_f16 v[118:121], v[234:237], v[150:153], v[118:121]
	v_mfma_f32_16x16x32_f16 v[114:117], v[242:245], v[150:153], v[114:117]
	v_mfma_f32_16x16x32_f16 v[102:105], v[234:237], v[158:161], v[102:105]
	v_mfma_f32_16x16x32_f16 v[98:101], v[242:245], v[158:161], v[98:101]
	v_mfma_f32_16x16x32_f16 v[86:89], v[234:237], v[192:195], v[86:89]
	v_mfma_f32_16x16x32_f16 v[82:85], v[242:245], v[192:195], v[82:85]
	v_mfma_f32_16x16x32_f16 v[70:73], v[234:237], v[200:203], v[70:73]
	v_mfma_f32_16x16x32_f16 v[66:69], v[242:245], v[200:203], v[66:69]
	s_mov_b32 m0, s71
	v_lshl_add_u64 v[170:171], s[50:51], 0, v[180:181]
	s_barrier
	ds_read_b128 v[146:149], v210 offset:16384
	ds_read_b128 v[150:153], v210 offset:17408
	ds_read_b128 v[154:157], v210 offset:18432
	ds_read_b128 v[158:161], v210 offset:19456
	ds_read_b128 v[188:191], v210 offset:20480
	ds_read_b128 v[192:195], v210 offset:21504
	ds_read_b128 v[196:199], v210 offset:22528
	ds_read_b128 v[200:203], v210 offset:23552
	global_load_lds_dwordx4 v[170:171], off
	v_lshl_add_u64 v[172:173], s[50:51], 0, v[176:177]
	s_mov_b32 m0, s61
	s_nop 0
	global_load_lds_dwordx4 v[172:173], off
	s_barrier
	s_waitcnt lgkmcnt(0)
	s_waitcnt lgkmcnt(0)
	v_mfma_f32_16x16x32_f16 v[62:65], v[122:125], v[146:149], v[62:65]
	v_mfma_f32_16x16x32_f16 v[58:61], v[138:141], v[146:149], v[58:61]
	v_mfma_f32_16x16x32_f16 v[46:49], v[122:125], v[154:157], v[46:49]
	v_mfma_f32_16x16x32_f16 v[42:45], v[138:141], v[154:157], v[42:45]
	v_mfma_f32_16x16x32_f16 v[30:33], v[122:125], v[188:191], v[30:33]
	v_mfma_f32_16x16x32_f16 v[26:29], v[138:141], v[188:191], v[26:29]
	v_mfma_f32_16x16x32_f16 v[14:17], v[122:125], v[196:199], v[14:17]
	v_mfma_f32_16x16x32_f16 v[10:13], v[138:141], v[196:199], v[10:13]
	v_mfma_f32_16x16x32_f16 v[62:65], v[126:129], v[150:153], v[62:65]
	v_mfma_f32_16x16x32_f16 v[58:61], v[142:145], v[150:153], v[58:61]
	v_mfma_f32_16x16x32_f16 v[46:49], v[126:129], v[158:161], v[46:49]
	v_mfma_f32_16x16x32_f16 v[42:45], v[142:145], v[158:161], v[42:45]
	v_mfma_f32_16x16x32_f16 v[30:33], v[126:129], v[192:195], v[30:33]
	v_mfma_f32_16x16x32_f16 v[26:29], v[142:145], v[192:195], v[26:29]
	v_mfma_f32_16x16x32_f16 v[14:17], v[126:129], v[200:203], v[14:17]
	v_mfma_f32_16x16x32_f16 v[10:13], v[142:145], v[200:203], v[10:13]
	s_barrier
	s_add_u32 s90, s48, 0x80000
	s_addc_u32 s91, s49, 0
	s_add_i32 s23, s23, s75
	s_mov_b32 m0, s23
	s_nop 0
	global_load_lds_dwordx4 v178, s[90:91]
	s_add_i32 m0, s23, 0x2000
	s_nop 0
	global_load_lds_dwordx4 v174, s[90:91]
	s_waitcnt vmcnt(6)
	s_barrier
; #define PG8_STAGE(bufoff, gbase, voff) do { _Pragma("unroll") for (int _i = 0; _i < 2; ++_i) \
;         __builtin_amdgcn_global_load_lds((const unsigned*)((const char*)(gbase) + (voff)[_i]), (LAS unsigned*)(lds + (bufoff) + ldsw + _i * 8192), 16, 0, 0); } while (0)
; #define PG8_LDA(dst, b, h) do { _Pragma("unroll") for (int m = 0; m < 4; ++m) _Pragma("unroll") for (int k = 0; k < 2; ++k) dst[m][k] = *(const LAS f16x8*)(lds + PG8_SA(b, h) + aoff + m * 2048 + k * 1024); } while (0)
; #define PG8_LDB(dst, b, h) do { _Pragma("unroll") for (int n = 0; n < 2; ++n) _Pragma("unroll") for (int k = 0; k < 2; ++k) dst[n][k] = *(const LAS f16x8*)(lds + PG8_SB(b, h) + boff + n * 2048 + k * 1024); } while (0)
; #define PG8_MMA(ai, bj, At, Bt) do { __builtin_amdgcn_s_setprio(1); _Pragma("unroll") for (int m = 0; m < 4; ++m) _Pragma("unroll") for (int n = 0; n < 2; ++n) _Pragma("unroll") for (int k = 0; k < 2; ++k) \
;         acc[ai][bj][m][n] = __builtin_amdgcn_mfma_f32_16x16x32_f16(Bt[n][k], At[m][k], acc[ai][bj][m][n], 0, 0, 0); __builtin_amdgcn_s_setprio(0); } while (0)
; #define PG8_WAIT_V(n) asm volatile("s_waitcnt vmcnt(" #n ")" ::: "memory")
; #define PG8_WAIT_L(n) asm volatile("s_waitcnt lgkmcnt(" #n ")" ::: "memory")
; #define PG8_BAR __builtin_amdgcn_s_barrier()
; #define PG8_SCHED __builtin_amdgcn_sched_barrier(0)
; template <class Epi>
; __device__ __forceinline__ void gemm_phase(LAS unsigned char* lds, const Gemm g0, const StaticOrder& S, const Epi& E) {
;     ...
;             PG8_WAIT_V(6); PG8_BAR; PG8_MMA(1, 1, At, B1); PG8_BAR;
;             PG8_LDB(B0, 1, 0); PG8_SCHED; PG8_LDA(At, 1, 0); PG8_STAGE(PG8_SA(0, 1), a2 + hstep, voffA);
;             PG8_WAIT_L(8); PG8_BAR; PG8_WAIT_L(0); PG8_MMA(0, 0, At, B0); PG8_BAR; PG8_SCHED;
;             PG8_LDB(B1, 1, 1); PG8_STAGE(PG8_SB(1, 0), b3, voffB);
;             PG8_BAR; PG8_WAIT_L(0); PG8_MMA(0, 1, At, B1); PG8_BAR;
	v_mfma_f32_16x16x32_f16 v[54:57], v[212:215], v[146:149], v[54:57]
	v_mfma_f32_16x16x32_f16 v[50:53], v[238:241], v[146:149], v[50:53]
	v_mfma_f32_16x16x32_f16 v[38:41], v[212:215], v[154:157], v[38:41]
	v_mfma_f32_16x16x32_f16 v[34:37], v[238:241], v[154:157], v[34:37]
	v_mfma_f32_16x16x32_f16 v[22:25], v[212:215], v[188:191], v[22:25]
	v_mfma_f32_16x16x32_f16 v[18:21], v[238:241], v[188:191], v[18:21]
	v_mfma_f32_16x16x32_f16 v[6:9], v[212:215], v[196:199], v[6:9]
	v_mfma_f32_16x16x32_f16 v[2:5], v[238:241], v[196:199], v[2:5]
	v_mfma_f32_16x16x32_f16 v[54:57], v[234:237], v[150:153], v[54:57]
	v_mfma_f32_16x16x32_f16 v[50:53], v[242:245], v[150:153], v[50:53]
	v_mfma_f32_16x16x32_f16 v[38:41], v[234:237], v[158:161], v[38:41]
	v_mfma_f32_16x16x32_f16 v[34:37], v[242:245], v[158:161], v[34:37]
	v_mfma_f32_16x16x32_f16 v[22:25], v[234:237], v[192:195], v[22:25]
	v_mfma_f32_16x16x32_f16 v[18:21], v[242:245], v[192:195], v[18:21]
	v_mfma_f32_16x16x32_f16 v[6:9], v[234:237], v[200:203], v[6:9]
	v_mfma_f32_16x16x32_f16 v[2:5], v[242:245], v[200:203], v[2:5]
	s_add_i32 s23, 0, 0x18000
	s_barrier
	ds_read_b128 v[122:125], v165 offset:32768
	ds_read_b128 v[126:129], v165 offset:33792
	ds_read_b128 v[138:141], v165 offset:34816
	ds_read_b128 v[142:145], v165 offset:35840
	s_add_u32 s50, s50, 0x80000
	s_addc_u32 s51, s51, 0
	s_mov_b32 m0, s74
	ds_read_b128 v[146:149], v210 offset:32768
	ds_read_b128 v[150:153], v210 offset:33792
	ds_read_b128 v[154:157], v210 offset:34816
	ds_read_b128 v[158:161], v210 offset:35840
	ds_read_b128 v[188:191], v210 offset:36864
	ds_read_b128 v[192:195], v210 offset:37888
	ds_read_b128 v[196:199], v210 offset:38912
	ds_read_b128 v[200:203], v210 offset:39936
	global_load_lds_dwordx4 v180, s[50:51]
	s_mov_b32 m0, s18
	s_nop 0
	global_load_lds_dwordx4 v176, s[50:51]
	s_waitcnt lgkmcnt(8)
	s_barrier
	s_waitcnt lgkmcnt(0)
	s_waitcnt lgkmcnt(0)
	v_mfma_f32_16x16x32_f16 v[134:137], v[122:125], v[146:149], v[134:137]
	v_mfma_f32_16x16x32_f16 v[130:133], v[138:141], v[146:149], v[130:133]
	v_mfma_f32_16x16x32_f16 v[110:113], v[122:125], v[154:157], v[110:113]
	v_mfma_f32_16x16x32_f16 v[106:109], v[138:141], v[154:157], v[106:109]
	v_mfma_f32_16x16x32_f16 v[94:97], v[122:125], v[188:191], v[94:97]
	v_mfma_f32_16x16x32_f16 v[90:93], v[138:141], v[188:191], v[90:93]
	v_mfma_f32_16x16x32_f16 v[78:81], v[122:125], v[196:199], v[78:81]
	v_mfma_f32_16x16x32_f16 v[74:77], v[138:141], v[196:199], v[74:77]
	v_mfma_f32_16x16x32_f16 v[134:137], v[126:129], v[150:153], v[134:137]
	v_mfma_f32_16x16x32_f16 v[130:133], v[142:145], v[150:153], v[130:133]
	v_mfma_f32_16x16x32_f16 v[110:113], v[126:129], v[158:161], v[110:113]
	v_mfma_f32_16x16x32_f16 v[106:109], v[142:145], v[158:161], v[106:109]
	v_mfma_f32_16x16x32_f16 v[94:97], v[126:129], v[192:195], v[94:97]
	v_mfma_f32_16x16x32_f16 v[90:93], v[142:145], v[192:195], v[90:93]
	v_mfma_f32_16x16x32_f16 v[78:81], v[126:129], v[200:203], v[78:81]
	v_mfma_f32_16x16x32_f16 v[74:77], v[142:145], v[200:203], v[74:77]
	s_barrier
	s_add_i32 s50, 0, 0x1c000
	s_add_i32 s23, s23, s75
	s_mov_b32 m0, s23
	ds_read_b128 v[212:215], v165 offset:49152
	ds_read_b128 v[234:237], v165 offset:50176
	ds_read_b128 v[238:241], v165 offset:51200
	ds_read_b128 v[242:245], v165 offset:52224
	global_load_lds_dwordx4 v162, s[48:49]
	s_add_i32 m0, s23, 0x2000
	s_nop 0
	global_load_lds_dwordx4 v164, s[48:49]
	s_barrier
	s_waitcnt lgkmcnt(0)
	s_waitcnt lgkmcnt(0)
	v_mfma_f32_16x16x32_f16 v[118:121], v[212:215], v[146:149], v[118:121]
	v_mfma_f32_16x16x32_f16 v[114:117], v[238:241], v[146:149], v[114:117]
	v_mfma_f32_16x16x32_f16 v[102:105], v[212:215], v[154:157], v[102:105]
	v_mfma_f32_16x16x32_f16 v[98:101], v[238:241], v[154:157], v[98:101]
	v_mfma_f32_16x16x32_f16 v[86:89], v[212:215], v[188:191], v[86:89]
	v_mfma_f32_16x16x32_f16 v[82:85], v[238:241], v[188:191], v[82:85]
	v_mfma_f32_16x16x32_f16 v[70:73], v[212:215], v[196:199], v[70:73]
	v_mfma_f32_16x16x32_f16 v[66:69], v[238:241], v[196:199], v[66:69]
	v_mfma_f32_16x16x32_f16 v[118:121], v[234:237], v[150:153], v[118:121]
	v_mfma_f32_16x16x32_f16 v[114:117], v[242:245], v[150:153], v[114:117]
	v_mfma_f32_16x16x32_f16 v[102:105], v[234:237], v[158:161], v[102:105]
	v_mfma_f32_16x16x32_f16 v[98:101], v[242:245], v[158:161], v[98:101]
	v_mfma_f32_16x16x32_f16 v[86:89], v[234:237], v[192:195], v[86:89]
	v_mfma_f32_16x16x32_f16 v[82:85], v[242:245], v[192:195], v[82:85]
	v_mfma_f32_16x16x32_f16 v[70:73], v[234:237], v[200:203], v[70:73]
	v_mfma_f32_16x16x32_f16 v[66:69], v[242:245], v[200:203], v[66:69]
	s_mov_b32 m0, s28
	v_lshl_add_u64 v[162:163], v[170:171], 0, s[64:65]
	s_barrier
; #define GAS __attribute__((address_space(1)))
; #define PG8_STAGE(bufoff, gbase, voff) do { _Pragma("unroll") for (int _i = 0; _i < 2; ++_i) \
;         __builtin_amdgcn_global_load_lds((const unsigned*)((const char*)(gbase) + (voff)[_i]), (LAS unsigned*)(lds + (bufoff) + ldsw + _i * 8192), 16, 0, 0); } while (0)
; #define PG8_LDA(dst, b, h) do { _Pragma("unroll") for (int m = 0; m < 4; ++m) _Pragma("unroll") for (int k = 0; k < 2; ++k) dst[m][k] = *(const LAS f16x8*)(lds + PG8_SA(b, h) + aoff + m * 2048 + k * 1024); } while (0)
; #define PG8_MMA(ai, bj, At, Bt) do { __builtin_amdgcn_s_setprio(1); _Pragma("unroll") for (int m = 0; m < 4; ++m) _Pragma("unroll") for (int n = 0; n < 2; ++n) _Pragma("unroll") for (int k = 0; k < 2; ++k) \
;         acc[ai][bj][m][n] = __builtin_amdgcn_mfma_f32_16x16x32_f16(Bt[n][k], At[m][k], acc[ai][bj][m][n], 0, 0, 0); __builtin_amdgcn_s_setprio(0); } while (0)
; #define PG8_WAIT_V(n) asm volatile("s_waitcnt vmcnt(" #n ")" ::: "memory")
; #define PG8_WAIT_L(n) asm volatile("s_waitcnt lgkmcnt(" #n ")" ::: "memory")
; #define PG8_BAR __builtin_amdgcn_s_barrier()
; #define PG8_SCHED __builtin_amdgcn_sched_barrier(0)
;     __device__ __forceinline__ void operator()(f32x4 (&acc)[2][2][4][2], const Unit& u, int wr, int wc, int fr, int fq) const {
;     ...
;         { const int lane = fr + 16 * fq, cL = u.pn * BM + wc * 32 + (lane < 32 ? lane : 96 + lane);
;           float vg = 0.f, vb = 0.f, vt = 0.f;
;           if (hasln) { vg = *(const GAS float*)(pg + cL); vb = *(const GAS float*)(pb + cL); }
;           if (haszh) vt = *(const GAS float*)(tg + cL);
; template <class Epi>
; __device__ __forceinline__ void gemm_phase(LAS unsigned char* lds, const Gemm g0, const StaticOrder& S, const Epi& E) {
;     ...
;             PG8_BAR; PG8_WAIT_L(0); PG8_MMA(0, 1, At, B1); PG8_BAR;
;             PG8_LDA(At, 1, 1); PG8_STAGE(PG8_SA(1, 0), a3, voffA);
;             PG8_BAR; PG8_WAIT_L(0); PG8_MMA(1, 0, At, B0); PG8_BAR; PG8_SCHED;
;             PG8_STAGE(PG8_SB(1, 1), b3 + hstep, voffB);
;             PG8_WAIT_V(6); PG8_BAR; PG8_MMA(1, 1, At, B1); PG8_BAR;
;         }
	ds_read_b128 v[146:149], v210 offset:49152
	ds_read_b128 v[150:153], v210 offset:50176
	ds_read_b128 v[154:157], v210 offset:51200
	ds_read_b128 v[158:161], v210 offset:52224
	ds_read_b128 v[188:191], v210 offset:53248
	ds_read_b128 v[192:195], v210 offset:54272
	ds_read_b128 v[196:199], v210 offset:55296
	ds_read_b128 v[200:203], v210 offset:56320
	global_load_lds_dwordx4 v[162:163], off
	v_lshl_add_u64 v[162:163], v[172:173], 0, s[64:65]
	s_mov_b32 m0, s29
	s_nop 0
	global_load_lds_dwordx4 v[162:163], off
	s_barrier
	s_waitcnt lgkmcnt(0)
	s_waitcnt lgkmcnt(0)
	v_mfma_f32_16x16x32_f16 v[62:65], v[122:125], v[146:149], v[62:65]
	v_mfma_f32_16x16x32_f16 v[58:61], v[138:141], v[146:149], v[58:61]
	v_mfma_f32_16x16x32_f16 v[46:49], v[122:125], v[154:157], v[46:49]
	v_mfma_f32_16x16x32_f16 v[42:45], v[138:141], v[154:157], v[42:45]
	v_mfma_f32_16x16x32_f16 v[30:33], v[122:125], v[188:191], v[30:33]
	v_mfma_f32_16x16x32_f16 v[26:29], v[138:141], v[188:191], v[26:29]
	v_mfma_f32_16x16x32_f16 v[14:17], v[122:125], v[196:199], v[14:17]
	v_mfma_f32_16x16x32_f16 v[10:13], v[138:141], v[196:199], v[10:13]
	v_mfma_f32_16x16x32_f16 v[62:65], v[126:129], v[150:153], v[62:65]
	v_mfma_f32_16x16x32_f16 v[58:61], v[142:145], v[150:153], v[58:61]
	v_mfma_f32_16x16x32_f16 v[46:49], v[126:129], v[158:161], v[46:49]
	v_mfma_f32_16x16x32_f16 v[42:45], v[142:145], v[158:161], v[42:45]
	v_mfma_f32_16x16x32_f16 v[30:33], v[126:129], v[192:195], v[30:33]
	v_mfma_f32_16x16x32_f16 v[26:29], v[142:145], v[192:195], v[26:29]
	v_mfma_f32_16x16x32_f16 v[14:17], v[126:129], v[200:203], v[14:17]
	v_mfma_f32_16x16x32_f16 v[10:13], v[142:145], v[200:203], v[10:13]
	s_barrier
	s_add_u32 s48, s48, 0x80080
	s_addc_u32 s49, s49, 0
	s_add_i32 s23, s50, s75
	s_mov_b32 m0, s23
	s_nop 0
	global_load_lds_dwordx4 v178, s[48:49]
	s_add_i32 m0, s23, 0x2000
	s_nop 0
	global_load_lds_dwordx4 v174, s[48:49]
	s_waitcnt vmcnt(6)
	s_barrier
	v_mfma_f32_16x16x32_f16 v[54:57], v[212:215], v[146:149], v[54:57]
	v_mfma_f32_16x16x32_f16 v[50:53], v[238:241], v[146:149], v[50:53]
	v_mfma_f32_16x16x32_f16 v[38:41], v[212:215], v[154:157], v[38:41]
	v_mfma_f32_16x16x32_f16 v[34:37], v[238:241], v[154:157], v[34:37]
	v_mfma_f32_16x16x32_f16 v[22:25], v[212:215], v[188:191], v[22:25]
	v_mfma_f32_16x16x32_f16 v[18:21], v[238:241], v[188:191], v[18:21]
	v_mfma_f32_16x16x32_f16 v[6:9], v[212:215], v[196:199], v[6:9]
	v_mfma_f32_16x16x32_f16 v[2:5], v[238:241], v[196:199], v[2:5]
	v_mfma_f32_16x16x32_f16 v[54:57], v[234:237], v[150:153], v[54:57]
	v_mfma_f32_16x16x32_f16 v[50:53], v[242:245], v[150:153], v[50:53]
	v_mfma_f32_16x16x32_f16 v[38:41], v[234:237], v[158:161], v[38:41]
	v_mfma_f32_16x16x32_f16 v[34:37], v[242:245], v[158:161], v[34:37]
	v_mfma_f32_16x16x32_f16 v[22:25], v[234:237], v[192:195], v[22:25]
	v_mfma_f32_16x16x32_f16 v[18:21], v[242:245], v[192:195], v[18:21]
	v_mfma_f32_16x16x32_f16 v[6:9], v[234:237], v[200:203], v[6:9]
	v_mfma_f32_16x16x32_f16 v[2:5], v[242:245], v[200:203], v[2:5]
	s_add_i32 s22, s22, 2
	s_add_u32 vcc_lo, vcc_lo, 0x100
	s_addc_u32 vcc_hi, vcc_hi, 0
	s_add_u32 s12, s12, 0x100
	s_addc_u32 s13, s13, 0
	s_cmp_gt_u32 s22, 29
	s_barrier
	s_cbranch_scc0 .LBB0_512
	s_lshl_b32 s12, s83, 8
	s_or_b32 s15, s12, s31
	v_add_u32_e32 v122, s15, v206
	v_cndmask_b32_e64 v124, 0, 1, s[44:45]
	v_ashrrev_i32_e32 v123, 31, v122
	v_mov_b32_e32 v196, 0
	v_cmp_ne_u32_e64 s[12:13], 1, v124
	s_andn2_b64 vcc, exec, s[44:45]
	v_mov_b32_e32 v124, 0
	v_mov_b32_e32 v125, 0
	s_cbranch_vccnz .LBB0_515
	v_lshlrev_b64 v[124:125], 2, v[122:123]
	v_lshl_add_u64 v[126:127], s[80:81], 0, v[124:125]
	v_lshl_add_u64 v[124:125], s[58:59], 0, v[124:125]
	global_load_dword v125, v[124:125], off
	s_nop 0
	global_load_dword v124, v[126:127], off

;     __device__ __forceinline__ void prefetch(const Unit& u, int wr, int wc, int lane) const { lnfold_prefetch(vl, stats, gW, bW, u, wr, wc, lane); }
;     __device__ __forceinline__ void prefetch(const Unit& u, int wr, int wc, int lane) const { lnfold_prefetch(vl, stats, gW, bW, u, wr, wc, lane); }
; #define PG8_STAGE(bufoff, gbase, voff) do { _Pragma("unroll") for (int _i = 0; _i < 2; ++_i) \
;         __builtin_amdgcn_global_load_lds((const unsigned*)((const char*)(gbase) + (voff)[_i]), (LAS unsigned*)(lds + (bufoff) + ldsw + _i * 8192), 16, 0, 0); } while (0)
; #define PG8_LDA(dst, b, h) do { _Pragma("unroll") for (int m = 0; m < 4; ++m) _Pragma("unroll") for (int k = 0; k < 2; ++k) dst[m][k] = *(const LAS f16x8*)(lds + PG8_SA(b, h) + aoff + m * 2048 + k * 1024); } while (0)
; #define PG8_LDB(dst, b, h) do { _Pragma("unroll") for (int n = 0; n < 2; ++n) _Pragma("unroll") for (int k = 0; k < 2; ++k) dst[n][k] = *(const LAS f16x8*)(lds + PG8_SB(b, h) + boff + n * 2048 + k * 1024); } while (0)
; #define PG8_WAIT_V(n) asm volatile("s_waitcnt vmcnt(" #n ")" ::: "memory")
; #define PG8_WAIT_L(n) asm volatile("s_waitcnt lgkmcnt(" #n ")" ::: "memory")
; #define PG8_BAR __builtin_amdgcn_s_barrier()
; template <class Epi>
; __device__ __forceinline__ void gemm_phase(LAS unsigned char* lds, const Gemm g0, const StaticOrder& S, const Epi& E) {
;     ...
;             const bool last = (t == nt - 2);
;             if (Epi::PREF && last) E.prefetch(cur, wr, wc, lane);
;             const char* a1 = cA + (size_t)(t + 1) * kstep;
;             const char* a2 = last ? nA : cA + (size_t)(t + 2) * kstep; const char* b2 = last ? nB : cB + (size_t)(t + 2) * kstep;
;             const char* a3 = a2 + kstep; const char* b3 = b2 + kstep;
;             PG8_LDB(B0, 0, 0); PG8_SCHED; PG8_LDA(At, 0, 0); PG8_STAGE(PG8_SA(1, 1), a1 + hstep, voffA);
;             PG8_WAIT_L(8); PG8_BAR; PG8_WAIT_L(0); PG8_MMA(0, 0, At, B0); PG8_BAR; PG8_SCHED;
;             PG8_LDB(B1, 0, 1); PG8_STAGE(PG8_SB(0, 0), b2, voffB);
;             PG8_BAR; PG8_WAIT_L(0); PG8_MMA(0, 1, At, B1); PG8_BAR;
;             PG8_LDA(At, 0, 1); PG8_STAGE(PG8_SA(0, 0), a2, voffA);
;             PG8_BAR; PG8_WAIT_L(0); PG8_MMA(1, 0, At, B0); PG8_BAR; PG8_SCHED;
;             PG8_STAGE(PG8_SB(0, 1), b2 + hstep, voffB);
;             PG8_WAIT_V(6); PG8_BAR; PG8_MMA(1, 1, At, B1); PG8_BAR;
.LBB0_620:
	s_add_u32 s58, s50, 0xfff80080
	s_addc_u32 s59, s51, -1
	s_and_b64 s[22:23], s[52:53], exec
	s_cselect_b32 s59, s37, s59
	s_cselect_b32 s58, s74, s58
	s_add_i32 s82, 0, 0x10000
	v_add_u32_e32 v187, s82, v189
	ds_read_b128 v[60:63], v187
	ds_read_b128 v[64:67], v187 offset:1024
	ds_read_b128 v[78:81], v187 offset:2048
	ds_read_b128 v[82:85], v187 offset:3072
	s_and_b64 s[22:23], s[52:53], exec
	s_cselect_b32 s53, s35, s25
	s_cselect_b32 s52, s75, s24
	s_add_i32 m0, s18, 0xc000
	ds_read_b128 v[86:89], v213
	ds_read_b128 v[90:93], v213 offset:1024
	ds_read_b128 v[194:197], v213 offset:2048
	ds_read_b128 v[234:237], v213 offset:3072
	ds_read_b128 v[238:241], v213 offset:4096
	ds_read_b128 v[242:245], v213 offset:5120
	ds_read_b128 v[246:249], v213 offset:6144
	ds_read_b128 v[226:229], v213 offset:7168
	global_load_lds_dwordx4 v184, s[50:51]
	s_add_i32 m0, s18, 0xe000
	s_nop 0
	global_load_lds_dwordx4 v182, s[50:51]
	s_waitcnt lgkmcnt(8)
	s_barrier
	s_waitcnt lgkmcnt(0)
	s_waitcnt lgkmcnt(0)
	v_mfma_f32_16x16x32_f16 v[158:161], v[60:63], v[86:89], v[158:161]
	v_mfma_f32_16x16x32_f16 v[150:153], v[78:81], v[86:89], v[150:153]
	v_mfma_f32_16x16x32_f16 v[142:145], v[60:63], v[194:197], v[142:145]
	v_mfma_f32_16x16x32_f16 v[134:137], v[78:81], v[194:197], v[134:137]
	v_mfma_f32_16x16x32_f16 v[126:129], v[60:63], v[238:241], v[126:129]
	v_mfma_f32_16x16x32_f16 v[118:121], v[78:81], v[238:241], v[118:121]
	v_mfma_f32_16x16x32_f16 v[110:113], v[60:63], v[246:249], v[110:113]
	v_mfma_f32_16x16x32_f16 v[102:105], v[78:81], v[246:249], v[102:105]
	v_mfma_f32_16x16x32_f16 v[158:161], v[64:67], v[90:93], v[158:161]
	v_mfma_f32_16x16x32_f16 v[150:153], v[82:85], v[90:93], v[150:153]
	v_mfma_f32_16x16x32_f16 v[142:145], v[64:67], v[234:237], v[142:145]
	v_mfma_f32_16x16x32_f16 v[134:137], v[82:85], v[234:237], v[134:137]
	v_mfma_f32_16x16x32_f16 v[126:129], v[64:67], v[242:245], v[126:129]
	v_mfma_f32_16x16x32_f16 v[118:121], v[82:85], v[242:245], v[118:121]
	v_mfma_f32_16x16x32_f16 v[110:113], v[64:67], v[226:229], v[110:113]
	v_mfma_f32_16x16x32_f16 v[102:105], v[82:85], v[226:229], v[102:105]
	s_barrier
	s_add_i32 s83, 0, 0x14000
	s_add_i32 s22, s82, s5
	v_add_u32_e32 v186, 0x80, v178
	s_mov_b32 m0, s22
	ds_read_b128 v[162:165], v187 offset:16384
	ds_read_b128 v[222:225], v187 offset:17408
	ds_read_b128 v[214:217], v187 offset:18432
	ds_read_b128 v[170:173], v187 offset:19456
	global_load_lds_dwordx4 v178, s[52:53]
	v_add_u32_e32 v190, 0x80, v174
	s_add_i32 m0, s22, 0x2000
	s_nop 0
	global_load_lds_dwordx4 v174, s[52:53]
	s_barrier
	s_waitcnt lgkmcnt(0)
	s_waitcnt lgkmcnt(0)
	v_mfma_f32_16x16x32_f16 v[154:157], v[162:165], v[86:89], v[154:157]
	v_mfma_f32_16x16x32_f16 v[86:89], v[214:217], v[86:89], v[146:149]
	v_mfma_f32_16x16x32_f16 v[130:133], v[214:217], v[194:197], v[130:133]
	v_mfma_f32_16x16x32_f16 v[122:125], v[162:165], v[238:241], v[122:125]
	v_mfma_f32_16x16x32_f16 v[114:117], v[214:217], v[238:241], v[114:117]
	v_mfma_f32_16x16x32_f16 v[106:109], v[162:165], v[246:249], v[106:109]
	v_mfma_f32_16x16x32_f16 v[98:101], v[214:217], v[246:249], v[98:101]
	v_mfma_f32_16x16x32_f16 v[154:157], v[222:225], v[90:93], v[154:157]
	v_mfma_f32_16x16x32_f16 v[86:89], v[170:173], v[90:93], v[86:89]
	v_mfma_f32_16x16x32_f16 v[90:93], v[162:165], v[194:197], v[138:141]
	v_mfma_f32_16x16x32_f16 v[130:133], v[170:173], v[234:237], v[130:133]
	v_mfma_f32_16x16x32_f16 v[122:125], v[222:225], v[242:245], v[122:125]
	v_mfma_f32_16x16x32_f16 v[114:117], v[170:173], v[242:245], v[114:117]
	v_mfma_f32_16x16x32_f16 v[106:109], v[222:225], v[226:229], v[106:109]
	v_mfma_f32_16x16x32_f16 v[98:101], v[170:173], v[226:229], v[98:101]
	v_mfma_f32_16x16x32_f16 v[90:93], v[222:225], v[234:237], v[90:93]
	s_mov_b32 m0, s18
	v_add_u32_e32 v198, 0x80, v180
	s_barrier
	ds_read_b128 v[138:141], v213 offset:16384
	ds_read_b128 v[146:149], v213 offset:17408
	ds_read_b128 v[194:197], v213 offset:18432
	ds_read_b128 v[226:229], v213 offset:19456
	ds_read_b128 v[234:237], v213 offset:20480
	ds_read_b128 v[238:241], v213 offset:21504
	ds_read_b128 v[242:245], v213 offset:22528
	ds_read_b128 v[246:249], v213 offset:23552
	global_load_lds_dwordx4 v180, s[58:59]
	v_add_u32_e32 v202, 0x80, v176
	s_mov_b32 m0, s19
	s_nop 0
	global_load_lds_dwordx4 v176, s[58:59]
	s_barrier
	s_waitcnt lgkmcnt(0)
	s_waitcnt lgkmcnt(0)
	v_mfma_f32_16x16x32_f16 v[94:97], v[60:63], v[138:141], v[94:97]
	v_mfma_f32_16x16x32_f16 v[68:71], v[78:81], v[138:141], v[70:73]
	v_mfma_f32_16x16x32_f16 v[46:49], v[60:63], v[194:197], v[46:49]
	v_mfma_f32_16x16x32_f16 v[38:41], v[78:81], v[194:197], v[38:41]
	v_mfma_f32_16x16x32_f16 v[30:33], v[60:63], v[234:237], v[30:33]
	v_mfma_f32_16x16x32_f16 v[22:25], v[78:81], v[234:237], v[22:25]
	v_mfma_f32_16x16x32_f16 v[14:17], v[60:63], v[242:245], v[14:17]
	v_mfma_f32_16x16x32_f16 v[6:9], v[78:81], v[242:245], v[6:9]
	v_mfma_f32_16x16x32_f16 v[94:97], v[64:67], v[146:149], v[94:97]
	v_mfma_f32_16x16x32_f16 v[68:71], v[82:85], v[146:149], v[68:71]
	v_mfma_f32_16x16x32_f16 v[46:49], v[64:67], v[226:229], v[46:49]
	v_mfma_f32_16x16x32_f16 v[38:41], v[82:85], v[226:229], v[38:41]
	v_mfma_f32_16x16x32_f16 v[30:33], v[64:67], v[238:241], v[30:33]
	v_mfma_f32_16x16x32_f16 v[22:25], v[82:85], v[238:241], v[22:25]
	v_mfma_f32_16x16x32_f16 v[14:17], v[64:67], v[246:249], v[14:17]
	v_mfma_f32_16x16x32_f16 v[6:9], v[82:85], v[246:249], v[6:9]
	s_barrier
	s_add_u32 s22, s52, 0x80000
	s_addc_u32 s23, s53, 0
	s_add_i32 s82, s83, s5
	s_mov_b32 m0, s82
	s_nop 0
	global_load_lds_dwordx4 v178, s[22:23]
	s_add_i32 m0, s82, 0x2000
	s_nop 0
	global_load_lds_dwordx4 v174, s[22:23]
	s_waitcnt vmcnt(6)
	s_barrier
; #define PG8_STAGE(bufoff, gbase, voff) do { _Pragma("unroll") for (int _i = 0; _i < 2; ++_i) \
;         __builtin_amdgcn_global_load_lds((const unsigned*)((const char*)(gbase) + (voff)[_i]), (LAS unsigned*)(lds + (bufoff) + ldsw + _i * 8192), 16, 0, 0); } while (0)
; #define PG8_LDA(dst, b, h) do { _Pragma("unroll") for (int m = 0; m < 4; ++m) _Pragma("unroll") for (int k = 0; k < 2; ++k) dst[m][k] = *(const LAS f16x8*)(lds + PG8_SA(b, h) + aoff + m * 2048 + k * 1024); } while (0)
; #define PG8_LDB(dst, b, h) do { _Pragma("unroll") for (int n = 0; n < 2; ++n) _Pragma("unroll") for (int k = 0; k < 2; ++k) dst[n][k] = *(const LAS f16x8*)(lds + PG8_SB(b, h) + boff + n * 2048 + k * 1024); } while (0)
; #define PG8_MMA(ai, bj, At, Bt) do { __builtin_amdgcn_s_setprio(1); _Pragma("unroll") for (int m = 0; m < 4; ++m) _Pragma("unroll") for (int n = 0; n < 2; ++n) _Pragma("unroll") for (int k = 0; k < 2; ++k) \
;         acc[ai][bj][m][n] = __builtin_amdgcn_mfma_f32_16x16x32_f16(Bt[n][k], At[m][k], acc[ai][bj][m][n], 0, 0, 0); __builtin_amdgcn_s_setprio(0); } while (0)
; #define PG8_WAIT_V(n) asm volatile("s_waitcnt vmcnt(" #n ")" ::: "memory")
; #define PG8_WAIT_L(n) asm volatile("s_waitcnt lgkmcnt(" #n ")" ::: "memory")
; #define PG8_BAR __builtin_amdgcn_s_barrier()
; #define PG8_SCHED __builtin_amdgcn_sched_barrier(0)
; template <class Epi>
; __device__ __forceinline__ void gemm_phase(LAS unsigned char* lds, const Gemm g0, const StaticOrder& S, const Epi& E) {
;     ...
;             PG8_WAIT_V(6); PG8_BAR; PG8_MMA(1, 1, At, B1); PG8_BAR;
;             PG8_LDB(B0, 1, 0); PG8_SCHED; PG8_LDA(At, 1, 0); PG8_STAGE(PG8_SA(0, 1), a2 + hstep, voffA);
;             PG8_WAIT_L(8); PG8_BAR; PG8_WAIT_L(0); PG8_MMA(0, 0, At, B0); PG8_BAR; PG8_SCHED;
;             PG8_LDB(B1, 1, 1); PG8_STAGE(PG8_SB(1, 0), b3, voffB);
;             PG8_BAR; PG8_WAIT_L(0); PG8_MMA(0, 1, At, B1); PG8_BAR;
	v_mfma_f32_16x16x32_f16 v[50:53], v[214:217], v[138:141], v[50:53]
	v_mfma_f32_16x16x32_f16 v[42:45], v[162:165], v[194:197], v[42:45]
	v_mfma_f32_16x16x32_f16 v[34:37], v[214:217], v[194:197], v[34:37]
	v_mfma_f32_16x16x32_f16 v[26:29], v[162:165], v[234:237], v[26:29]
	v_mfma_f32_16x16x32_f16 v[18:21], v[214:217], v[234:237], v[18:21]
	v_mfma_f32_16x16x32_f16 v[10:13], v[162:165], v[242:245], v[10:13]
	v_mfma_f32_16x16x32_f16 v[2:5], v[214:217], v[242:245], v[2:5]
	v_mfma_f32_16x16x32_f16 v[60:63], v[162:165], v[138:141], v[74:77]
	v_mfma_f32_16x16x32_f16 v[50:53], v[170:173], v[146:149], v[50:53]
	v_mfma_f32_16x16x32_f16 v[42:45], v[222:225], v[226:229], v[42:45]
	v_mfma_f32_16x16x32_f16 v[34:37], v[170:173], v[226:229], v[34:37]
	v_mfma_f32_16x16x32_f16 v[26:29], v[222:225], v[238:241], v[26:29]
	v_mfma_f32_16x16x32_f16 v[18:21], v[170:173], v[238:241], v[18:21]
	v_mfma_f32_16x16x32_f16 v[10:13], v[222:225], v[246:249], v[10:13]
	v_mfma_f32_16x16x32_f16 v[2:5], v[170:173], v[246:249], v[2:5]
	v_mfma_f32_16x16x32_f16 v[60:63], v[222:225], v[146:149], v[60:63]
	s_add_i32 s82, 0, 0x18000
	s_barrier
	ds_read_b128 v[64:67], v187 offset:32768
	ds_read_b128 v[74:77], v187 offset:33792
	ds_read_b128 v[78:81], v187 offset:34816
	ds_read_b128 v[82:85], v187 offset:35840
	s_add_u32 s22, s58, 0x80000
	s_addc_u32 s23, s59, 0
	s_mov_b32 m0, s28
	ds_read_b128 v[138:141], v213 offset:32768
	ds_read_b128 v[146:149], v213 offset:33792
	ds_read_b128 v[162:165], v213 offset:34816
	ds_read_b128 v[170:173], v213 offset:35840
	ds_read_b128 v[194:197], v213 offset:36864
	ds_read_b128 v[214:217], v213 offset:37888
	ds_read_b128 v[222:225], v213 offset:38912
	ds_read_b128 v[226:229], v213 offset:39936
	global_load_lds_dwordx4 v180, s[22:23]
	s_mov_b32 m0, s29
	s_nop 0
	global_load_lds_dwordx4 v176, s[22:23]
	s_waitcnt lgkmcnt(8)
	s_barrier
	s_waitcnt lgkmcnt(0)
	s_waitcnt lgkmcnt(0)
	v_mfma_f32_16x16x32_f16 v[158:161], v[64:67], v[138:141], v[158:161]
	v_mfma_f32_16x16x32_f16 v[150:153], v[78:81], v[138:141], v[150:153]
	v_mfma_f32_16x16x32_f16 v[142:145], v[64:67], v[162:165], v[142:145]
	v_mfma_f32_16x16x32_f16 v[134:137], v[78:81], v[162:165], v[134:137]
	v_mfma_f32_16x16x32_f16 v[126:129], v[64:67], v[194:197], v[126:129]
	v_mfma_f32_16x16x32_f16 v[118:121], v[78:81], v[194:197], v[118:121]
	v_mfma_f32_16x16x32_f16 v[110:113], v[64:67], v[222:225], v[110:113]
	v_mfma_f32_16x16x32_f16 v[102:105], v[78:81], v[222:225], v[102:105]
	v_mfma_f32_16x16x32_f16 v[158:161], v[74:77], v[146:149], v[158:161]
	v_mfma_f32_16x16x32_f16 v[150:153], v[82:85], v[146:149], v[150:153]
	v_mfma_f32_16x16x32_f16 v[142:145], v[74:77], v[170:173], v[142:145]
	v_mfma_f32_16x16x32_f16 v[134:137], v[82:85], v[170:173], v[134:137]
	v_mfma_f32_16x16x32_f16 v[126:129], v[74:77], v[214:217], v[126:129]
	v_mfma_f32_16x16x32_f16 v[118:121], v[82:85], v[214:217], v[118:121]
	v_mfma_f32_16x16x32_f16 v[110:113], v[74:77], v[226:229], v[110:113]
	v_mfma_f32_16x16x32_f16 v[102:105], v[82:85], v[226:229], v[102:105]
	s_barrier
	s_add_i32 s83, 0, 0x1c000
	s_add_i32 s22, s82, s5
	ds_read_b128 v[234:237], v187 offset:49152
	ds_read_b128 v[238:241], v187 offset:50176
	ds_read_b128 v[242:245], v187 offset:51200
	ds_read_b128 v[246:249], v187 offset:52224
	s_mov_b32 m0, s22
	s_nop 0
	global_load_lds_dwordx4 v186, s[52:53]
	s_add_i32 m0, s22, 0x2000
	s_nop 0
	global_load_lds_dwordx4 v190, s[52:53]
	s_barrier
; #define PG8_STAGE(bufoff, gbase, voff) do { _Pragma("unroll") for (int _i = 0; _i < 2; ++_i) \
;         __builtin_amdgcn_global_load_lds((const unsigned*)((const char*)(gbase) + (voff)[_i]), (LAS unsigned*)(lds + (bufoff) + ldsw + _i * 8192), 16, 0, 0); } while (0)
; #define PG8_LDA(dst, b, h) do { _Pragma("unroll") for (int m = 0; m < 4; ++m) _Pragma("unroll") for (int k = 0; k < 2; ++k) dst[m][k] = *(const LAS f16x8*)(lds + PG8_SA(b, h) + aoff + m * 2048 + k * 1024); } while (0)
; #define PG8_MMA(ai, bj, At, Bt) do { __builtin_amdgcn_s_setprio(1); _Pragma("unroll") for (int m = 0; m < 4; ++m) _Pragma("unroll") for (int n = 0; n < 2; ++n) _Pragma("unroll") for (int k = 0; k < 2; ++k) \
;         acc[ai][bj][m][n] = __builtin_amdgcn_mfma_f32_16x16x32_f16(Bt[n][k], At[m][k], acc[ai][bj][m][n], 0, 0, 0); __builtin_amdgcn_s_setprio(0); } while (0)
; #define PG8_WAIT_V(n) asm volatile("s_waitcnt vmcnt(" #n ")" ::: "memory")
; #define PG8_WAIT_L(n) asm volatile("s_waitcnt lgkmcnt(" #n ")" ::: "memory")
; #define PG8_BAR __builtin_amdgcn_s_barrier()
; #define PG8_SCHED __builtin_amdgcn_sched_barrier(0)
; template <class Epi>
; __device__ __forceinline__ void gemm_phase(LAS unsigned char* lds, const Gemm g0, const StaticOrder& S, const Epi& E) {
;     ...
;             PG8_BAR; PG8_WAIT_L(0); PG8_MMA(0, 1, At, B1); PG8_BAR;
;             PG8_LDA(At, 1, 1); PG8_STAGE(PG8_SA(1, 0), a3, voffA);
;             PG8_BAR; PG8_WAIT_L(0); PG8_MMA(1, 0, At, B0); PG8_BAR; PG8_SCHED;
;             PG8_STAGE(PG8_SB(1, 1), b3 + hstep, voffB);
;             PG8_WAIT_V(6); PG8_BAR; PG8_MMA(1, 1, At, B1); PG8_BAR;
;         }
	s_waitcnt lgkmcnt(0)
	s_waitcnt lgkmcnt(0)
	v_mfma_f32_16x16x32_f16 v[154:157], v[234:237], v[138:141], v[154:157]
	v_mfma_f32_16x16x32_f16 v[86:89], v[242:245], v[138:141], v[86:89]
	v_mfma_f32_16x16x32_f16 v[154:157], v[238:241], v[146:149], v[154:157]
	v_mfma_f32_16x16x32_f16 v[146:149], v[246:249], v[146:149], v[86:89]
	v_mfma_f32_16x16x32_f16 v[86:89], v[234:237], v[162:165], v[90:93]
	v_mfma_f32_16x16x32_f16 v[138:141], v[238:241], v[170:173], v[86:89]
	v_mfma_f32_16x16x32_f16 v[86:89], v[242:245], v[162:165], v[130:133]
	v_mfma_f32_16x16x32_f16 v[130:133], v[246:249], v[170:173], v[86:89]
	v_mfma_f32_16x16x32_f16 v[86:89], v[234:237], v[194:197], v[122:125]
	v_mfma_f32_16x16x32_f16 v[122:125], v[238:241], v[214:217], v[86:89]
	v_mfma_f32_16x16x32_f16 v[86:89], v[242:245], v[194:197], v[114:117]
	v_mfma_f32_16x16x32_f16 v[114:117], v[246:249], v[214:217], v[86:89]
	v_mfma_f32_16x16x32_f16 v[86:89], v[234:237], v[222:225], v[106:109]
	v_mfma_f32_16x16x32_f16 v[106:109], v[238:241], v[226:229], v[86:89]
	v_mfma_f32_16x16x32_f16 v[86:89], v[242:245], v[222:225], v[98:101]
	v_mfma_f32_16x16x32_f16 v[98:101], v[246:249], v[226:229], v[86:89]
	s_mov_b32 m0, s31
	s_barrier
	s_nop 2
	ds_read_b128 v[86:89], v213 offset:49152
	ds_read_b128 v[90:93], v213 offset:50176
	ds_read_b128 v[162:165], v213 offset:51200
	ds_read_b128 v[170:173], v213 offset:52224
	ds_read_b128 v[194:197], v213 offset:53248
	ds_read_b128 v[214:217], v213 offset:54272
	ds_read_b128 v[222:225], v213 offset:55296
	ds_read_b128 v[226:229], v213 offset:56320
	global_load_lds_dwordx4 v198, s[58:59]
	s_mov_b32 m0, s61
	s_nop 0
	global_load_lds_dwordx4 v202, s[58:59]
	s_barrier
	s_waitcnt lgkmcnt(0)
	s_waitcnt lgkmcnt(0)
	v_mfma_f32_16x16x32_f16 v[94:97], v[64:67], v[86:89], v[94:97]
	v_mfma_f32_16x16x32_f16 v[68:71], v[78:81], v[86:89], v[68:71]
	v_mfma_f32_16x16x32_f16 v[46:49], v[64:67], v[162:165], v[46:49]
	v_mfma_f32_16x16x32_f16 v[38:41], v[78:81], v[162:165], v[38:41]
	v_mfma_f32_16x16x32_f16 v[30:33], v[64:67], v[194:197], v[30:33]
	v_mfma_f32_16x16x32_f16 v[22:25], v[78:81], v[194:197], v[22:25]
	v_mfma_f32_16x16x32_f16 v[14:17], v[64:67], v[222:225], v[14:17]
	v_mfma_f32_16x16x32_f16 v[6:9], v[78:81], v[222:225], v[6:9]
	v_mfma_f32_16x16x32_f16 v[94:97], v[74:77], v[90:93], v[94:97]
	v_mfma_f32_16x16x32_f16 v[70:73], v[82:85], v[90:93], v[68:71]
	v_mfma_f32_16x16x32_f16 v[46:49], v[74:77], v[170:173], v[46:49]
	v_mfma_f32_16x16x32_f16 v[38:41], v[82:85], v[170:173], v[38:41]
	v_mfma_f32_16x16x32_f16 v[30:33], v[74:77], v[214:217], v[30:33]
	v_mfma_f32_16x16x32_f16 v[22:25], v[82:85], v[214:217], v[22:25]
	v_mfma_f32_16x16x32_f16 v[14:17], v[74:77], v[226:229], v[14:17]
	v_mfma_f32_16x16x32_f16 v[6:9], v[82:85], v[226:229], v[6:9]
	s_barrier
	s_add_u32 s22, s52, 0x80080
	s_addc_u32 s23, s53, 0
	s_add_i32 s52, s83, s5
	s_mov_b32 m0, s52
	s_nop 0
	global_load_lds_dwordx4 v178, s[22:23]
	s_add_i32 m0, s52, 0x2000
	s_nop 0
	global_load_lds_dwordx4 v174, s[22:23]
	s_waitcnt vmcnt(6)
	s_barrier
	v_mfma_f32_16x16x32_f16 v[60:63], v[234:237], v[86:89], v[60:63]
	v_mfma_f32_16x16x32_f16 v[50:53], v[242:245], v[86:89], v[50:53]
	v_mfma_f32_16x16x32_f16 v[42:45], v[234:237], v[162:165], v[42:45]
	v_mfma_f32_16x16x32_f16 v[34:37], v[242:245], v[162:165], v[34:37]
	v_mfma_f32_16x16x32_f16 v[26:29], v[234:237], v[194:197], v[26:29]
	v_mfma_f32_16x16x32_f16 v[18:21], v[242:245], v[194:197], v[18:21]
	v_mfma_f32_16x16x32_f16 v[10:13], v[234:237], v[222:225], v[10:13]
	v_mfma_f32_16x16x32_f16 v[2:5], v[242:245], v[222:225], v[2:5]
	v_mfma_f32_16x16x32_f16 v[74:77], v[238:241], v[90:93], v[60:63]
	v_mfma_f32_16x16x32_f16 v[50:53], v[246:249], v[90:93], v[50:53]
	v_mfma_f32_16x16x32_f16 v[42:45], v[238:241], v[170:173], v[42:45]
	v_mfma_f32_16x16x32_f16 v[34:37], v[246:249], v[170:173], v[34:37]
	v_mfma_f32_16x16x32_f16 v[26:29], v[238:241], v[214:217], v[26:29]
	v_mfma_f32_16x16x32_f16 v[18:21], v[246:249], v[214:217], v[18:21]
	v_mfma_f32_16x16x32_f16 v[10:13], v[238:241], v[226:229], v[10:13]
	v_mfma_f32_16x16x32_f16 v[2:5], v[246:249], v[226:229], v[2:5]
	s_add_i32 s81, s81, 2
	s_add_u32 s24, s24, 0x100
	s_addc_u32 s25, s25, 0
	s_add_u32 s50, s50, 0x100
	s_addc_u32 s51, s51, 0
	s_cmp_gt_u32 s81, 29
	s_barrier
	s_cbranch_scc1 .LBB0_616

;     __device__ __forceinline__ void prefetch(const Unit& u, int wr, int wc, int lane) const { lnfold_prefetch(vl, stats, gW, bW, u, wr, wc, lane); }
;     __device__ __forceinline__ void prefetch(const Unit& u, int wr, int wc, int lane) const { lnfold_prefetch(vl, stats, gW, bW, u, wr, wc, lane); }
; #define PG8_STAGE(bufoff, gbase, voff) do { _Pragma("unroll") for (int _i = 0; _i < 2; ++_i) \
;         __builtin_amdgcn_global_load_lds((const unsigned*)((const char*)(gbase) + (voff)[_i]), (LAS unsigned*)(lds + (bufoff) + ldsw + _i * 8192), 16, 0, 0); } while (0)
; #define PG8_LDA(dst, b, h) do { _Pragma("unroll") for (int m = 0; m < 4; ++m) _Pragma("unroll") for (int k = 0; k < 2; ++k) dst[m][k] = *(const LAS f16x8*)(lds + PG8_SA(b, h) + aoff + m * 2048 + k * 1024); } while (0)
; #define PG8_LDB(dst, b, h) do { _Pragma("unroll") for (int n = 0; n < 2; ++n) _Pragma("unroll") for (int k = 0; k < 2; ++k) dst[n][k] = *(const LAS f16x8*)(lds + PG8_SB(b, h) + boff + n * 2048 + k * 1024); } while (0)
; #define PG8_WAIT_V(n) asm volatile("s_waitcnt vmcnt(" #n ")" ::: "memory")
; #define PG8_WAIT_L(n) asm volatile("s_waitcnt lgkmcnt(" #n ")" ::: "memory")
; #define PG8_BAR __builtin_amdgcn_s_barrier()
; template <class Epi>
; __device__ __forceinline__ void gemm_phase(LAS unsigned char* lds, const Gemm g0, const StaticOrder& S, const Epi& E) {
;     ...
;             const bool last = (t == nt - 2);
;             if (Epi::PREF && last) E.prefetch(cur, wr, wc, lane);
;             const char* a1 = cA + (size_t)(t + 1) * kstep;
;             const char* a2 = last ? nA : cA + (size_t)(t + 2) * kstep; const char* b2 = last ? nB : cB + (size_t)(t + 2) * kstep;
;             const char* a3 = a2 + kstep; const char* b3 = b2 + kstep;
;             PG8_LDB(B0, 0, 0); PG8_SCHED; PG8_LDA(At, 0, 0); PG8_STAGE(PG8_SA(1, 1), a1 + hstep, voffA);
;             PG8_WAIT_L(8); PG8_BAR; PG8_WAIT_L(0); PG8_MMA(0, 0, At, B0); PG8_BAR; PG8_SCHED;
;             PG8_LDB(B1, 0, 1); PG8_STAGE(PG8_SB(0, 0), b2, voffB);
;             PG8_BAR; PG8_WAIT_L(0); PG8_MMA(0, 1, At, B1); PG8_BAR;
;             PG8_LDA(At, 0, 1); PG8_STAGE(PG8_SA(0, 0), a2, voffA);
;             PG8_BAR; PG8_WAIT_L(0); PG8_MMA(1, 0, At, B0); PG8_BAR; PG8_SCHED;
;             PG8_STAGE(PG8_SB(0, 1), b2 + hstep, voffB);
;             PG8_WAIT_V(6); PG8_BAR; PG8_MMA(1, 1, At, B1); PG8_BAR;
.LBB0_672:
	s_add_u32 s10, s12, 0x100
	s_addc_u32 s11, s13, 0
	s_add_i32 s23, 0, 0x10000
	v_add_u32_e32 v201, s23, v203
	ds_read_b128 v[130:133], v201
	ds_read_b128 v[134:137], v201 offset:1024
	ds_read_b128 v[138:141], v201 offset:2048
	ds_read_b128 v[142:145], v201 offset:3072
	s_cmpk_eq_i32 s22, 0x54
	s_cselect_b32 s81, s1, s11
	s_cselect_b32 s80, s0, s10
	s_cselect_b32 s63, s59, s25
	s_cselect_b32 s62, s58, s24
	s_add_i32 m0, s28, 0xc000
	ds_read_b128 v[146:149], v208
	ds_read_b128 v[150:153], v208 offset:1024
	ds_read_b128 v[154:157], v208 offset:2048
	ds_read_b128 v[162:165], v208 offset:3072
	ds_read_b128 v[170:173], v208 offset:4096
	ds_read_b128 v[184:187], v208 offset:5120
	ds_read_b128 v[188:191], v208 offset:6144
	ds_read_b128 v[192:195], v208 offset:7168
	global_load_lds_dwordx4 v182, s[12:13]
	s_add_i32 m0, s28, 0xe000
	s_nop 0
	global_load_lds_dwordx4 v180, s[12:13]
	s_waitcnt lgkmcnt(8)
	s_barrier
	s_waitcnt lgkmcnt(0)
	s_waitcnt lgkmcnt(0)
	v_mfma_f32_16x16x32_f16 v[126:129], v[130:133], v[146:149], v[126:129]
	v_mfma_f32_16x16x32_f16 v[122:125], v[138:141], v[146:149], v[122:125]
	v_mfma_f32_16x16x32_f16 v[110:113], v[130:133], v[154:157], v[110:113]
	v_mfma_f32_16x16x32_f16 v[106:109], v[138:141], v[154:157], v[106:109]
	v_mfma_f32_16x16x32_f16 v[94:97], v[130:133], v[170:173], v[94:97]
	v_mfma_f32_16x16x32_f16 v[90:93], v[138:141], v[170:173], v[90:93]
	v_mfma_f32_16x16x32_f16 v[78:81], v[130:133], v[188:191], v[78:81]
	v_mfma_f32_16x16x32_f16 v[74:77], v[138:141], v[188:191], v[74:77]
	v_mfma_f32_16x16x32_f16 v[126:129], v[134:137], v[150:153], v[126:129]
	v_mfma_f32_16x16x32_f16 v[122:125], v[142:145], v[150:153], v[122:125]
	v_mfma_f32_16x16x32_f16 v[110:113], v[134:137], v[162:165], v[110:113]
	v_mfma_f32_16x16x32_f16 v[106:109], v[142:145], v[162:165], v[106:109]
	v_mfma_f32_16x16x32_f16 v[94:97], v[134:137], v[184:187], v[94:97]
	v_mfma_f32_16x16x32_f16 v[90:93], v[142:145], v[184:187], v[90:93]
	v_mfma_f32_16x16x32_f16 v[78:81], v[134:137], v[192:195], v[78:81]
	v_mfma_f32_16x16x32_f16 v[74:77], v[142:145], v[192:195], v[74:77]
	s_barrier
	s_add_i32 s90, 0, 0x14000
	s_add_i32 s12, s23, s19
	ds_read_b128 v[196:199], v201 offset:16384
	ds_read_b128 v[210:213], v201 offset:17408
	ds_read_b128 v[214:217], v201 offset:18432
	ds_read_b128 v[222:225], v201 offset:19456
	v_add_u32_e32 v200, 0x80, v174
	s_mov_b32 m0, s12
	v_add_u32_e32 v218, 0x80, v158
	global_load_lds_dwordx4 v174, s[62:63]
	s_add_i32 m0, s12, 0x2000
	s_nop 0
	global_load_lds_dwordx4 v158, s[62:63]
	s_barrier
	s_waitcnt lgkmcnt(0)
	s_waitcnt lgkmcnt(0)
	v_mfma_f32_16x16x32_f16 v[118:121], v[196:199], v[146:149], v[118:121]
	v_mfma_f32_16x16x32_f16 v[114:117], v[214:217], v[146:149], v[114:117]
	v_mfma_f32_16x16x32_f16 v[102:105], v[196:199], v[154:157], v[102:105]
	v_mfma_f32_16x16x32_f16 v[98:101], v[214:217], v[154:157], v[98:101]
	v_mfma_f32_16x16x32_f16 v[86:89], v[196:199], v[170:173], v[86:89]
	v_mfma_f32_16x16x32_f16 v[82:85], v[214:217], v[170:173], v[82:85]
	v_mfma_f32_16x16x32_f16 v[70:73], v[196:199], v[188:191], v[70:73]
	v_mfma_f32_16x16x32_f16 v[66:69], v[214:217], v[188:191], v[66:69]
	v_mfma_f32_16x16x32_f16 v[118:121], v[210:213], v[150:153], v[118:121]
	v_mfma_f32_16x16x32_f16 v[114:117], v[222:225], v[150:153], v[114:117]
	v_mfma_f32_16x16x32_f16 v[102:105], v[210:213], v[162:165], v[102:105]
	v_mfma_f32_16x16x32_f16 v[98:101], v[222:225], v[162:165], v[98:101]
	v_mfma_f32_16x16x32_f16 v[86:89], v[210:213], v[184:187], v[86:89]
	v_mfma_f32_16x16x32_f16 v[82:85], v[222:225], v[184:187], v[82:85]
	v_mfma_f32_16x16x32_f16 v[70:73], v[210:213], v[192:195], v[70:73]
	v_mfma_f32_16x16x32_f16 v[66:69], v[222:225], v[192:195], v[66:69]
	s_mov_b32 m0, s28
	v_add_u32_e32 v226, 0x80, v176
	s_barrier
	ds_read_b128 v[146:149], v208 offset:16384
	ds_read_b128 v[150:153], v208 offset:17408
	ds_read_b128 v[154:157], v208 offset:18432
	ds_read_b128 v[162:165], v208 offset:19456
	ds_read_b128 v[170:173], v208 offset:20480
	ds_read_b128 v[184:187], v208 offset:21504
	ds_read_b128 v[188:191], v208 offset:22528
	ds_read_b128 v[192:195], v208 offset:23552
	global_load_lds_dwordx4 v176, s[80:81]
	v_add_u32_e32 v228, 0x80, v160
	s_mov_b32 m0, s29
	s_nop 0
	global_load_lds_dwordx4 v160, s[80:81]
	s_barrier
	s_waitcnt lgkmcnt(0)
	s_waitcnt lgkmcnt(0)
	v_mfma_f32_16x16x32_f16 v[62:65], v[130:133], v[146:149], v[62:65]
	v_mfma_f32_16x16x32_f16 v[58:61], v[138:141], v[146:149], v[58:61]
	v_mfma_f32_16x16x32_f16 v[46:49], v[130:133], v[154:157], v[46:49]
	v_mfma_f32_16x16x32_f16 v[42:45], v[138:141], v[154:157], v[42:45]
	v_mfma_f32_16x16x32_f16 v[30:33], v[130:133], v[170:173], v[30:33]
	v_mfma_f32_16x16x32_f16 v[26:29], v[138:141], v[170:173], v[26:29]
	v_mfma_f32_16x16x32_f16 v[14:17], v[130:133], v[188:191], v[14:17]
	v_mfma_f32_16x16x32_f16 v[10:13], v[138:141], v[188:191], v[10:13]
	v_mfma_f32_16x16x32_f16 v[62:65], v[134:137], v[150:153], v[62:65]
	v_mfma_f32_16x16x32_f16 v[58:61], v[142:145], v[150:153], v[58:61]
	v_mfma_f32_16x16x32_f16 v[46:49], v[134:137], v[162:165], v[46:49]
	v_mfma_f32_16x16x32_f16 v[42:45], v[142:145], v[162:165], v[42:45]
	v_mfma_f32_16x16x32_f16 v[30:33], v[134:137], v[184:187], v[30:33]
	v_mfma_f32_16x16x32_f16 v[26:29], v[142:145], v[184:187], v[26:29]
	v_mfma_f32_16x16x32_f16 v[14:17], v[134:137], v[192:195], v[14:17]
	v_mfma_f32_16x16x32_f16 v[10:13], v[142:145], v[192:195], v[10:13]
	s_barrier
	s_add_u32 s12, s62, 0x160000
	s_addc_u32 s13, s63, 0
	s_add_i32 s23, s90, s19
	s_mov_b32 m0, s23
	s_nop 0
	global_load_lds_dwordx4 v174, s[12:13]
	s_add_i32 m0, s23, 0x2000
	s_nop 0
	global_load_lds_dwordx4 v158, s[12:13]
	s_waitcnt vmcnt(6)
	s_barrier
; #define PG8_STAGE(bufoff, gbase, voff) do { _Pragma("unroll") for (int _i = 0; _i < 2; ++_i) \
;         __builtin_amdgcn_global_load_lds((const unsigned*)((const char*)(gbase) + (voff)[_i]), (LAS unsigned*)(lds + (bufoff) + ldsw + _i * 8192), 16, 0, 0); } while (0)
; #define PG8_LDA(dst, b, h) do { _Pragma("unroll") for (int m = 0; m < 4; ++m) _Pragma("unroll") for (int k = 0; k < 2; ++k) dst[m][k] = *(const LAS f16x8*)(lds + PG8_SA(b, h) + aoff + m * 2048 + k * 1024); } while (0)
; #define PG8_LDB(dst, b, h) do { _Pragma("unroll") for (int n = 0; n < 2; ++n) _Pragma("unroll") for (int k = 0; k < 2; ++k) dst[n][k] = *(const LAS f16x8*)(lds + PG8_SB(b, h) + boff + n * 2048 + k * 1024); } while (0)
; #define PG8_MMA(ai, bj, At, Bt) do { __builtin_amdgcn_s_setprio(1); _Pragma("unroll") for (int m = 0; m < 4; ++m) _Pragma("unroll") for (int n = 0; n < 2; ++n) _Pragma("unroll") for (int k = 0; k < 2; ++k) \
;         acc[ai][bj][m][n] = __builtin_amdgcn_mfma_f32_16x16x32_f16(Bt[n][k], At[m][k], acc[ai][bj][m][n], 0, 0, 0); __builtin_amdgcn_s_setprio(0); } while (0)
; #define PG8_WAIT_V(n) asm volatile("s_waitcnt vmcnt(" #n ")" ::: "memory")
; #define PG8_WAIT_L(n) asm volatile("s_waitcnt lgkmcnt(" #n ")" ::: "memory")
; #define PG8_BAR __builtin_amdgcn_s_barrier()
; #define PG8_SCHED __builtin_amdgcn_sched_barrier(0)
; template <class Epi>
; __device__ __forceinline__ void gemm_phase(LAS unsigned char* lds, const Gemm g0, const StaticOrder& S, const Epi& E) {
;     ...
;             PG8_WAIT_V(6); PG8_BAR; PG8_MMA(1, 1, At, B1); PG8_BAR;
;             PG8_LDB(B0, 1, 0); PG8_SCHED; PG8_LDA(At, 1, 0); PG8_STAGE(PG8_SA(0, 1), a2 + hstep, voffA);
;             PG8_WAIT_L(8); PG8_BAR; PG8_WAIT_L(0); PG8_MMA(0, 0, At, B0); PG8_BAR; PG8_SCHED;
;             PG8_LDB(B1, 1, 1); PG8_STAGE(PG8_SB(1, 0), b3, voffB);
;             PG8_BAR; PG8_WAIT_L(0); PG8_MMA(0, 1, At, B1); PG8_BAR;
	v_mfma_f32_16x16x32_f16 v[54:57], v[196:199], v[146:149], v[54:57]
	v_mfma_f32_16x16x32_f16 v[50:53], v[214:217], v[146:149], v[50:53]
	v_mfma_f32_16x16x32_f16 v[38:41], v[196:199], v[154:157], v[38:41]
	v_mfma_f32_16x16x32_f16 v[34:37], v[214:217], v[154:157], v[34:37]
	v_mfma_f32_16x16x32_f16 v[22:25], v[196:199], v[170:173], v[22:25]
	v_mfma_f32_16x16x32_f16 v[18:21], v[214:217], v[170:173], v[18:21]
	v_mfma_f32_16x16x32_f16 v[6:9], v[196:199], v[188:191], v[6:9]
	v_mfma_f32_16x16x32_f16 v[2:5], v[214:217], v[188:191], v[2:5]
	v_mfma_f32_16x16x32_f16 v[54:57], v[210:213], v[150:153], v[54:57]
	v_mfma_f32_16x16x32_f16 v[50:53], v[222:225], v[150:153], v[50:53]
	v_mfma_f32_16x16x32_f16 v[38:41], v[210:213], v[162:165], v[38:41]
	v_mfma_f32_16x16x32_f16 v[34:37], v[222:225], v[162:165], v[34:37]
	v_mfma_f32_16x16x32_f16 v[22:25], v[210:213], v[184:187], v[22:25]
	v_mfma_f32_16x16x32_f16 v[18:21], v[222:225], v[184:187], v[18:21]
	v_mfma_f32_16x16x32_f16 v[6:9], v[210:213], v[192:195], v[6:9]
	v_mfma_f32_16x16x32_f16 v[2:5], v[222:225], v[192:195], v[2:5]
	s_add_i32 s23, 0, 0x18000
	s_barrier
	ds_read_b128 v[130:133], v201 offset:32768
	ds_read_b128 v[134:137], v201 offset:33792
	ds_read_b128 v[138:141], v201 offset:34816
	ds_read_b128 v[142:145], v201 offset:35840
	s_add_u32 s12, s80, 0x160000
	s_addc_u32 s13, s81, 0
	s_mov_b32 m0, s31
	ds_read_b128 v[146:149], v208 offset:32768
	ds_read_b128 v[150:153], v208 offset:33792
	ds_read_b128 v[154:157], v208 offset:34816
	ds_read_b128 v[162:165], v208 offset:35840
	ds_read_b128 v[170:173], v208 offset:36864
	ds_read_b128 v[184:187], v208 offset:37888
	ds_read_b128 v[188:191], v208 offset:38912
	ds_read_b128 v[192:195], v208 offset:39936
	global_load_lds_dwordx4 v176, s[12:13]
	s_mov_b32 m0, s61
	s_nop 0
	global_load_lds_dwordx4 v160, s[12:13]
	s_waitcnt lgkmcnt(8)
	s_barrier
	s_waitcnt lgkmcnt(0)
	s_waitcnt lgkmcnt(0)
	v_mfma_f32_16x16x32_f16 v[126:129], v[130:133], v[146:149], v[126:129]
	v_mfma_f32_16x16x32_f16 v[122:125], v[138:141], v[146:149], v[122:125]
	v_mfma_f32_16x16x32_f16 v[110:113], v[130:133], v[154:157], v[110:113]
	v_mfma_f32_16x16x32_f16 v[106:109], v[138:141], v[154:157], v[106:109]
	v_mfma_f32_16x16x32_f16 v[94:97], v[130:133], v[170:173], v[94:97]
	v_mfma_f32_16x16x32_f16 v[90:93], v[138:141], v[170:173], v[90:93]
	v_mfma_f32_16x16x32_f16 v[78:81], v[130:133], v[188:191], v[78:81]
	v_mfma_f32_16x16x32_f16 v[74:77], v[138:141], v[188:191], v[74:77]
	v_mfma_f32_16x16x32_f16 v[126:129], v[134:137], v[150:153], v[126:129]
	v_mfma_f32_16x16x32_f16 v[122:125], v[142:145], v[150:153], v[122:125]
	v_mfma_f32_16x16x32_f16 v[110:113], v[134:137], v[162:165], v[110:113]
	v_mfma_f32_16x16x32_f16 v[106:109], v[142:145], v[162:165], v[106:109]
	v_mfma_f32_16x16x32_f16 v[94:97], v[134:137], v[184:187], v[94:97]
	v_mfma_f32_16x16x32_f16 v[90:93], v[142:145], v[184:187], v[90:93]
	v_mfma_f32_16x16x32_f16 v[78:81], v[134:137], v[192:195], v[78:81]
	v_mfma_f32_16x16x32_f16 v[74:77], v[142:145], v[192:195], v[74:77]
	s_barrier
	s_add_i32 s90, 0, 0x1c000
	s_add_i32 s12, s23, s19
	s_mov_b32 m0, s12
	ds_read_b128 v[196:199], v201 offset:49152
	ds_read_b128 v[210:213], v201 offset:50176
	ds_read_b128 v[214:217], v201 offset:51200
	ds_read_b128 v[222:225], v201 offset:52224
	global_load_lds_dwordx4 v200, s[62:63]
	s_add_i32 m0, s12, 0x2000
	s_nop 0
	global_load_lds_dwordx4 v218, s[62:63]
	s_barrier
	s_waitcnt lgkmcnt(0)
	s_waitcnt lgkmcnt(0)
	v_mfma_f32_16x16x32_f16 v[118:121], v[196:199], v[146:149], v[118:121]
	v_mfma_f32_16x16x32_f16 v[114:117], v[214:217], v[146:149], v[114:117]
	v_mfma_f32_16x16x32_f16 v[102:105], v[196:199], v[154:157], v[102:105]
	v_mfma_f32_16x16x32_f16 v[98:101], v[214:217], v[154:157], v[98:101]
	v_mfma_f32_16x16x32_f16 v[86:89], v[196:199], v[170:173], v[86:89]
	v_mfma_f32_16x16x32_f16 v[82:85], v[214:217], v[170:173], v[82:85]
	v_mfma_f32_16x16x32_f16 v[70:73], v[196:199], v[188:191], v[70:73]
	v_mfma_f32_16x16x32_f16 v[66:69], v[214:217], v[188:191], v[66:69]
	v_mfma_f32_16x16x32_f16 v[118:121], v[210:213], v[150:153], v[118:121]
	v_mfma_f32_16x16x32_f16 v[114:117], v[222:225], v[150:153], v[114:117]
	v_mfma_f32_16x16x32_f16 v[102:105], v[210:213], v[162:165], v[102:105]
	v_mfma_f32_16x16x32_f16 v[98:101], v[222:225], v[162:165], v[98:101]
	v_mfma_f32_16x16x32_f16 v[86:89], v[210:213], v[184:187], v[86:89]
	v_mfma_f32_16x16x32_f16 v[82:85], v[222:225], v[184:187], v[82:85]
	v_mfma_f32_16x16x32_f16 v[70:73], v[210:213], v[192:195], v[70:73]
	v_mfma_f32_16x16x32_f16 v[66:69], v[222:225], v[192:195], v[66:69]
	s_mov_b32 m0, s83
	s_barrier
; #define GAS __attribute__((address_space(1)))
; #define PG8_STAGE(bufoff, gbase, voff) do { _Pragma("unroll") for (int _i = 0; _i < 2; ++_i) \
;         __builtin_amdgcn_global_load_lds((const unsigned*)((const char*)(gbase) + (voff)[_i]), (LAS unsigned*)(lds + (bufoff) + ldsw + _i * 8192), 16, 0, 0); } while (0)
; #define PG8_LDA(dst, b, h) do { _Pragma("unroll") for (int m = 0; m < 4; ++m) _Pragma("unroll") for (int k = 0; k < 2; ++k) dst[m][k] = *(const LAS f16x8*)(lds + PG8_SA(b, h) + aoff + m * 2048 + k * 1024); } while (0)
; #define PG8_MMA(ai, bj, At, Bt) do { __builtin_amdgcn_s_setprio(1); _Pragma("unroll") for (int m = 0; m < 4; ++m) _Pragma("unroll") for (int n = 0; n < 2; ++n) _Pragma("unroll") for (int k = 0; k < 2; ++k) \
;         acc[ai][bj][m][n] = __builtin_amdgcn_mfma_f32_16x16x32_f16(Bt[n][k], At[m][k], acc[ai][bj][m][n], 0, 0, 0); __builtin_amdgcn_s_setprio(0); } while (0)
; #define PG8_WAIT_V(n) asm volatile("s_waitcnt vmcnt(" #n ")" ::: "memory")
; #define PG8_WAIT_L(n) asm volatile("s_waitcnt lgkmcnt(" #n ")" ::: "memory")
; #define PG8_BAR __builtin_amdgcn_s_barrier()
; #define PG8_SCHED __builtin_amdgcn_sched_barrier(0)
;     __device__ __forceinline__ void operator()(f32x4 (&acc)[2][2][4][2], const Unit& u, int wr, int wc, int fr, int fq) const {
;     ...
;         { const int lane = fr + 16 * fq, cL = u.pn * BM + wc * 32 + (lane < 32 ? lane : 96 + lane);
;           float vg = 0.f, vb = 0.f, vt = 0.f;
;           if (hasln) { vg = *(const GAS float*)(pg + cL); vb = *(const GAS float*)(pb + cL); }
;           if (haszh) vt = *(const GAS float*)(tg + cL);
; template <class Epi>
; __device__ __forceinline__ void gemm_phase(LAS unsigned char* lds, const Gemm g0, const StaticOrder& S, const Epi& E) {
;     ...
;             PG8_LDA(At, 1, 1); PG8_STAGE(PG8_SA(1, 0), a3, voffA);
;             PG8_BAR; PG8_WAIT_L(0); PG8_MMA(1, 0, At, B0); PG8_BAR; PG8_SCHED;
;             PG8_STAGE(PG8_SB(1, 1), b3 + hstep, voffB);
;             PG8_WAIT_V(6); PG8_BAR; PG8_MMA(1, 1, At, B1); PG8_BAR;
;         }
	ds_read_b128 v[146:149], v208 offset:49152
	ds_read_b128 v[150:153], v208 offset:50176
	ds_read_b128 v[154:157], v208 offset:51200
	ds_read_b128 v[162:165], v208 offset:52224
	ds_read_b128 v[170:173], v208 offset:53248
	ds_read_b128 v[184:187], v208 offset:54272
	ds_read_b128 v[188:191], v208 offset:55296
	ds_read_b128 v[192:195], v208 offset:56320
	global_load_lds_dwordx4 v226, s[80:81]
	s_mov_b32 m0, s84
	s_nop 0
	global_load_lds_dwordx4 v228, s[80:81]
	s_barrier
	s_waitcnt lgkmcnt(0)
	s_waitcnt lgkmcnt(0)
	v_mfma_f32_16x16x32_f16 v[62:65], v[130:133], v[146:149], v[62:65]
	v_mfma_f32_16x16x32_f16 v[58:61], v[138:141], v[146:149], v[58:61]
	v_mfma_f32_16x16x32_f16 v[46:49], v[130:133], v[154:157], v[46:49]
	v_mfma_f32_16x16x32_f16 v[42:45], v[138:141], v[154:157], v[42:45]
	v_mfma_f32_16x16x32_f16 v[30:33], v[130:133], v[170:173], v[30:33]
	v_mfma_f32_16x16x32_f16 v[26:29], v[138:141], v[170:173], v[26:29]
	v_mfma_f32_16x16x32_f16 v[14:17], v[130:133], v[188:191], v[14:17]
	v_mfma_f32_16x16x32_f16 v[10:13], v[138:141], v[188:191], v[10:13]
	v_mfma_f32_16x16x32_f16 v[62:65], v[134:137], v[150:153], v[62:65]
	v_mfma_f32_16x16x32_f16 v[58:61], v[142:145], v[150:153], v[58:61]
	v_mfma_f32_16x16x32_f16 v[46:49], v[134:137], v[162:165], v[46:49]
	v_mfma_f32_16x16x32_f16 v[42:45], v[142:145], v[162:165], v[42:45]
	v_mfma_f32_16x16x32_f16 v[30:33], v[134:137], v[184:187], v[30:33]
	v_mfma_f32_16x16x32_f16 v[26:29], v[142:145], v[184:187], v[26:29]
	v_mfma_f32_16x16x32_f16 v[14:17], v[134:137], v[192:195], v[14:17]
	v_mfma_f32_16x16x32_f16 v[10:13], v[142:145], v[192:195], v[10:13]
	s_barrier
	s_add_u32 s12, s62, 0x160080
	s_addc_u32 s13, s63, 0
	s_add_i32 s23, s90, s19
	s_mov_b32 m0, s23
	s_nop 0
	global_load_lds_dwordx4 v174, s[12:13]
	s_add_i32 m0, s23, 0x2000
	s_nop 0
	global_load_lds_dwordx4 v158, s[12:13]
	s_waitcnt vmcnt(6)
	s_barrier
	v_mfma_f32_16x16x32_f16 v[54:57], v[196:199], v[146:149], v[54:57]
	v_mfma_f32_16x16x32_f16 v[50:53], v[214:217], v[146:149], v[50:53]
	v_mfma_f32_16x16x32_f16 v[38:41], v[196:199], v[154:157], v[38:41]
	v_mfma_f32_16x16x32_f16 v[34:37], v[214:217], v[154:157], v[34:37]
	v_mfma_f32_16x16x32_f16 v[22:25], v[196:199], v[170:173], v[22:25]
	v_mfma_f32_16x16x32_f16 v[18:21], v[214:217], v[170:173], v[18:21]
	v_mfma_f32_16x16x32_f16 v[6:9], v[196:199], v[188:191], v[6:9]
	v_mfma_f32_16x16x32_f16 v[2:5], v[214:217], v[188:191], v[2:5]
	v_mfma_f32_16x16x32_f16 v[54:57], v[210:213], v[150:153], v[54:57]
	v_mfma_f32_16x16x32_f16 v[50:53], v[222:225], v[150:153], v[50:53]
	v_mfma_f32_16x16x32_f16 v[38:41], v[210:213], v[162:165], v[38:41]
	v_mfma_f32_16x16x32_f16 v[34:37], v[222:225], v[162:165], v[34:37]
	v_mfma_f32_16x16x32_f16 v[22:25], v[210:213], v[184:187], v[22:25]
	v_mfma_f32_16x16x32_f16 v[18:21], v[222:225], v[184:187], v[18:21]
	v_mfma_f32_16x16x32_f16 v[6:9], v[210:213], v[192:195], v[6:9]
	v_mfma_f32_16x16x32_f16 v[2:5], v[222:225], v[192:195], v[2:5]
	s_add_i32 s22, s22, 2
	s_add_u32 s24, s24, 0x100
	s_addc_u32 s25, s25, 0
	s_cmpk_gt_u32 s22, 0x55
	s_mov_b64 s[12:13], s[10:11]
	s_barrier
	s_cbranch_scc0 .LBB0_672
	s_lshl_b32 s10, s92, 8
	s_or_b32 s12, s10, s82
	v_add_u32_e32 v130, s12, v204
	v_ashrrev_i32_e32 v131, 31, v130
	v_lshlrev_b64 v[132:133], 2, v[130:131]
	v_lshl_add_u64 v[134:135], s[38:39], 0, v[132:133]
	v_lshl_add_u64 v[132:133], s[48:49], 0, v[132:133]
	global_load_dword v146, v[134:135], off
	global_load_dword v147, v[132:133], off
	v_readlane_b32 s22, v254, 55
	v_readlane_b32 s23, v254, 56
	s_andn2_b64 vcc, exec, s[22:23]
	v_mov_b32_e32 v148, 0
	v_cndmask_b32_e64 v132, 0, 1, s[22:23]
	v_cmp_ne_u32_e64 s[10:11], 1, v132
	s_cbranch_vccnz .LBB0_675
	v_lshl_add_u64 v[130:131], v[130:131], 2, s[50:51]
	global_load_dword v148, v[130:131], off
